# static priority raise for waves 0-3 applied to the P5 gate-mix GEMM too (16 per-block s_setprio flips removed from its K-loop); P5/P6 loop heads pinned at their offsets
# speedup vs baseline: 1.0074x; 1.0032x over previous
; #define PG8_STAGE(bufoff, gbase, voff) do { _Pragma("unroll") for (int _i = 0; _i < 2; ++_i) \
;         __builtin_amdgcn_global_load_lds((const unsigned*)((const char*)(gbase) + (voff)[_i]), (PG8_LAS unsigned*)(lds + (bufoff) + ldsw + _i * 8192), 16, 0, 0); } while (0)
; #define PG8_WAIT_V(n) asm volatile("s_waitcnt vmcnt(" #n ")" ::: "memory")
; #define PG8_BAR __builtin_amdgcn_s_barrier()
; template <class Epi, class Sched, bool ALIGN_EPI = false, bool SP2 = false>
; __device__ __forceinline__ void gemm_phase(PG8_LAS unsigned char* lds, const Gemm g, const Sched& S, const Epi& E) {
;     const int tid = threadIdx.x, wid = __builtin_amdgcn_readfirstlane(tid >> 6), lane = tid & 63, wr = wid >> 2, wc = wid & 3, fr = lane & 15, fq = lane >> 4;
;     ...
;         PG8_STAGE(PG8_SB(1, 0), cB + kstep, voffB); PG8_STAGE(PG8_SA(1, 0), cA + kstep, voffA); PG8_STAGE(PG8_SB(1, 1), cB + hstep + kstep, voffB);
;         PG8_WAIT_V(6); PG8_BAR;
.LBB0_617:
	s_add_u32 s65, s34, 0x24000000
	s_addc_u32 s66, s35, 0
	s_lshl_b32 s8, s8, 5
	s_and_b32 s14, s8, 0x60
	s_mov_b64 s[8:9], 0x80
	s_add_i32 m0, s59, 0x18000
	v_lshl_add_u64 v[8:9], v[8:9], 0, s[8:9]
	s_lshl_b32 s67, s1, 6
	s_lshl_b32 s1, s1, 13
	s_lshl_b32 s11, s14, 7
	s_waitcnt vmcnt(2)
	s_barrier
	global_load_lds_dwordx4 v[8:9], off
	v_lshl_add_u64 v[6:7], v[6:7], 0, s[8:9]
	s_add_i32 m0, s59, 0x1a000
	s_add_i32 s68, s59, 0x8000
	s_add_i32 s69, s59, 0xa000
	global_load_lds_dwordx4 v[6:7], off
	v_lshl_add_u64 v[2:3], v[2:3], 0, s[8:9]
	s_mov_b32 m0, s68
	s_add_u32 s12, s50, 0x80080
	global_load_lds_dwordx4 v[2:3], off
	v_lshl_add_u64 v[2:3], v[4:5], 0, s[8:9]
	s_mov_b32 m0, s69
	s_addc_u32 s13, s51, 0
	global_load_lds_dwordx4 v[2:3], off
	s_add_i32 m0, s59, 0x1c000
	v_lshl_add_u64 v[2:3], s[12:13], 0, v[134:135]
	global_load_lds_dwordx4 v[2:3], off
	v_lshl_add_u64 v[2:3], s[12:13], 0, v[138:139]
	s_add_i32 m0, s59, 0x1e000
	s_sext_i32_i8 s49, s0
	global_load_lds_dwordx4 v[2:3], off
	v_and_b32_e32 v154, 15, v220
	v_lshlrev_b32_e32 v2, 1, v13
	v_lshlrev_b32_e32 v4, 2, v220
	v_lshlrev_b32_e32 v5, 6, v220
	s_movk_i32 s0, 0x3c0
	v_lshl_or_b32 v3, v154, 6, v2
	v_and_b32_e32 v4, 32, v4
	v_and_or_b32 v2, v5, s0, v2
	v_bitop3_b32 v156, s11, v2, v4 bitop3:0xf6
	v_lshlrev_b32_e32 v2, 9, v220
	v_bitop3_b32 v3, v3, s1, v4 bitop3:0xde
	v_and_b32_e32 v2, 0x70000, v2
	v_lshlrev_b32_e32 v4, 12, v0
	v_or3_b32 v0, v10, v2, v4
	s_mov_b64 s[0:1], 0x80080
	v_add_u32_e32 v0, v0, v11
	v_lshl_add_u64 v[140:141], v[0:1], 0, s[0:1]
	v_lshlrev_b32_e32 v0, 5, v12
	v_and_b32_e32 v0, 0xf0000, v0
	s_waitcnt vmcnt(6)
	v_or3_b32 v0, v10, v0, v4
	s_cmpk_lt_u32 s10, 0x100
	v_add_u32_e32 v0, v0, v11
	v_or_b32_e32 v155, s67, v154
	s_mov_b32 s70, 0x18000
	s_mov_b32 s71, 0x8000
	s_cselect_b64 s[10:11], -1, 0
	v_or_b32_e32 v157, s14, v13
	s_waitcnt lgkmcnt(0)
	s_ashr_i32 s72, s33, 31
	v_lshl_add_u64 v[142:143], v[0:1], 0, s[0:1]
	v_mov_b64_e32 v[144:145], 0x400
	v_mov_b64_e32 v[146:147], 0x3ff
	s_mov_b32 s73, 0xc1f00000
	s_mov_b64 s[12:13], 0x8000
	s_mov_b32 s74, 0x8008000
	s_mov_b64 s[14:15], 0x10000
	s_mov_b32 s75, 0x8010000
	s_mov_b64 s[16:17], 0x18000
	s_mov_b32 s76, 0x8018000
	s_mov_b64 s[18:19], 0x40000
	s_mov_b32 s77, 0x40000
	s_mov_b32 s78, 0x8040000
	s_mov_b64 s[20:21], 0x48000
	s_mov_b32 s79, 0x48000
	s_mov_b32 s80, 0x8048000
	s_mov_b64 s[22:23], 0x50000
	s_mov_b32 s81, 0x50000
	s_mov_b32 s82, 0x8050000
	s_mov_b64 s[24:25], 0x58000
	s_mov_b32 s83, 0x58000
	s_mov_b32 s84, 0x8058000
	s_add_i32 s85, 0, 0x14000
	v_add_u32_e32 v158, 0, v3
	s_movk_i32 s86, 0x378
	s_movk_i32 s87, 0x3f8
	v_mov_b32_e32 v159, 0x41f00000
	v_mov_b32_e32 v160, 0x80
	s_barrier
	v_readfirstlane_b32 s101, v220
	s_nop 3
	s_lshr_b32 s101, s101, 6
	s_cmp_lt_u32 s101, 4
	s_cbranch_scc0 .Lprio_skip_p5
	s_setprio 1

; #define PG8_STAGE(bufoff, gbase, voff) do { _Pragma("unroll") for (int _i = 0; _i < 2; ++_i) \
;         __builtin_amdgcn_global_load_lds((const unsigned*)((const char*)(gbase) + (voff)[_i]), (PG8_LAS unsigned*)(lds + (bufoff) + ldsw + _i * 8192), 16, 0, 0); } while (0)
; #define PG8_LDA(dst, b, h) do { _Pragma("unroll") for (int m = 0; m < 4; ++m) _Pragma("unroll") for (int k = 0; k < 2; ++k) dst[m][k] = *(const PG8_LAS bf16x8*)(lds + PG8_SA(b, h) + aoff + m * 2048 + k * 1024); } while (0)
; #define PG8_LDB(dst, b, h) do { _Pragma("unroll") for (int n = 0; n < 2; ++n) _Pragma("unroll") for (int k = 0; k < 2; ++k) dst[n][k] = *(const PG8_LAS bf16x8*)(lds + PG8_SB(b, h) + boff + n * 2048 + k * 1024); } while (0)
; #define PG8_WAIT_V(n) asm volatile("s_waitcnt vmcnt(" #n ")" ::: "memory")
; #define PG8_WAIT_L(n) asm volatile("s_waitcnt lgkmcnt(" #n ")" ::: "memory")
; #define PG8_BAR __builtin_amdgcn_s_barrier()
; #define PG8_SCHED __builtin_amdgcn_sched_barrier(0)
; template <class Epi, class Sched, bool ALIGN_EPI = false, bool SP2 = false>
; __device__ __forceinline__ void gemm_phase(PG8_LAS unsigned char* lds, const Gemm g, const Sched& S, const Epi& E) {
;     ...
;         const bool has_next = S.next(ui + 1, nxt);
;         const char* nA = has_next ? (const char*)g.A + (size_t)nxt.pm * tstep : cA; const char* nB = has_next ? (const char*)g.Bt + (size_t)nxt.pn * tstep : cB;
;         for (int t = 0; t < nt; t += 2) {
;             const bool last = (t == nt - 2);
;             const char* a1 = cA + (size_t)(t + 1) * kstep;
;             const char* a2 = last ? nA : cA + (size_t)(t + 2) * kstep; const char* b2 = last ? nB : cB + (size_t)(t + 2) * kstep;
;             const char* a3 = a2 + kstep; const char* b3 = b2 + kstep;
;             if (last && has_next) S.a_ready(nxt);
;             if constexpr (Epi::MID) { if (t == (nt >> 1)) E.mid(acc, cur, wr, wc, fr, fq); }
;             if constexpr (SP2) {
;             PG8_LDB(B0, 0, 0); PG8_LDB(B1, 0, 1); PG8_SCHED; PG8_LDA(At, 0, 0); PG8_STAGE(PG8_SA(1, 1), a1 + hstep, voffA);
;             PG8_WAIT_V(8); PG8_WAIT_L(0); PG8_BAR; PG8_MMA(0, 0, At, B0); PG8_MMA(0, 1, At, B1); PG8_BAR; PG8_SCHED;
;             PG8_LDA(At, 0, 1); PG8_STAGE(PG8_SB(0, 0), b2, voffB); PG8_STAGE(PG8_SB(0, 1), b2 + hstep, voffB); PG8_STAGE(PG8_SA(0, 0), a2, voffA);
.LBB0_627:
	s_add_u32 s52, s46, s50
	s_addc_u32 s53, s47, s51
	s_add_u32 s52, s52, 0x100
	s_addc_u32 s53, s53, 0
	s_add_u32 s96, s93, s50
	s_addc_u32 s97, s94, s51
	s_cmpk_eq_i32 s50, 0xf00
	s_cselect_b32 s55, s41, s53
	s_cselect_b32 s54, s88, s52
	s_cselect_b32 s53, s90, s97
	s_cselect_b32 s52, s91, s96
	s_add_i32 s96, 0, 0x10000
	v_add_u32_e32 v0, s96, v156
	ds_read_b128 v[162:165], v0
	ds_read_b128 v[166:169], v0 offset:1024
	ds_read_b128 v[170:173], v0 offset:2048
	ds_read_b128 v[174:177], v0 offset:3072
	v_add_u32_e32 v0, s85, v156
	ds_read_b128 v[178:181], v0
	ds_read_b128 v[182:185], v0 offset:1024
	ds_read_b128 v[186:189], v0 offset:2048
	ds_read_b128 v[190:193], v0 offset:3072
	v_lshl_add_u64 v[2:3], v[150:151], 0, s[50:51]
	s_add_i32 m0, s59, 0xc000
	ds_read_b128 v[194:197], v158
	ds_read_b128 v[198:201], v158 offset:1024
	ds_read_b128 v[202:205], v158 offset:2048
	ds_read_b128 v[206:209], v158 offset:3072
	ds_read_b128 v[210:213], v158 offset:4096
	ds_read_b128 v[214:217], v158 offset:5120
	ds_read_b128 v[222:225], v158 offset:6144
	ds_read_b128 v[226:229], v158 offset:7168
	global_load_lds_dwordx4 v[2:3], off
	v_lshl_add_u64 v[2:3], v[152:153], 0, s[50:51]
	s_add_i32 m0, s59, 0xe000
	s_nop 0
	global_load_lds_dwordx4 v[2:3], off
	s_waitcnt vmcnt(8)
	s_waitcnt lgkmcnt(0)
	s_barrier
	s_waitcnt lgkmcnt(0)
	v_mfma_f32_16x16x32_bf16 v[128:131], v[162:165], v[194:197], v[128:131]
	v_mfma_f32_16x16x32_bf16 v[124:127], v[170:173], v[194:197], v[124:127]
	v_mfma_f32_16x16x32_bf16 v[112:115], v[162:165], v[202:205], v[112:115]
	v_mfma_f32_16x16x32_bf16 v[108:111], v[170:173], v[202:205], v[108:111]
	v_mfma_f32_16x16x32_bf16 v[96:99], v[162:165], v[210:213], v[96:99]
	v_mfma_f32_16x16x32_bf16 v[92:95], v[170:173], v[210:213], v[92:95]
	v_mfma_f32_16x16x32_bf16 v[80:83], v[162:165], v[222:225], v[80:83]
	v_mfma_f32_16x16x32_bf16 v[76:79], v[170:173], v[222:225], v[76:79]
	v_mfma_f32_16x16x32_bf16 v[128:131], v[166:169], v[198:201], v[128:131]
	v_mfma_f32_16x16x32_bf16 v[124:127], v[174:177], v[198:201], v[124:127]
	v_mfma_f32_16x16x32_bf16 v[112:115], v[166:169], v[206:209], v[112:115]
	v_mfma_f32_16x16x32_bf16 v[108:111], v[174:177], v[206:209], v[108:111]
	v_mfma_f32_16x16x32_bf16 v[96:99], v[166:169], v[214:217], v[96:99]
	v_mfma_f32_16x16x32_bf16 v[92:95], v[174:177], v[214:217], v[92:95]
	v_mfma_f32_16x16x32_bf16 v[80:83], v[166:169], v[226:229], v[80:83]
	v_mfma_f32_16x16x32_bf16 v[76:79], v[174:177], v[226:229], v[76:79]
	v_mfma_f32_16x16x32_bf16 v[120:123], v[178:181], v[194:197], v[120:123]
	v_mfma_f32_16x16x32_bf16 v[116:119], v[186:189], v[194:197], v[116:119]
	v_mfma_f32_16x16x32_bf16 v[104:107], v[178:181], v[202:205], v[104:107]
	v_mfma_f32_16x16x32_bf16 v[100:103], v[186:189], v[202:205], v[100:103]
	v_mfma_f32_16x16x32_bf16 v[88:91], v[178:181], v[210:213], v[88:91]
	v_mfma_f32_16x16x32_bf16 v[84:87], v[186:189], v[210:213], v[84:87]
	v_mfma_f32_16x16x32_bf16 v[72:75], v[178:181], v[222:225], v[72:75]
	v_mfma_f32_16x16x32_bf16 v[68:71], v[186:189], v[222:225], v[68:71]
	v_mfma_f32_16x16x32_bf16 v[120:123], v[182:185], v[198:201], v[120:123]
	v_mfma_f32_16x16x32_bf16 v[116:119], v[190:193], v[198:201], v[116:119]
	v_mfma_f32_16x16x32_bf16 v[104:107], v[182:185], v[206:209], v[104:107]
	v_mfma_f32_16x16x32_bf16 v[100:103], v[190:193], v[206:209], v[100:103]
	v_mfma_f32_16x16x32_bf16 v[88:91], v[182:185], v[214:217], v[88:91]
	v_mfma_f32_16x16x32_bf16 v[84:87], v[190:193], v[214:217], v[84:87]
	v_mfma_f32_16x16x32_bf16 v[72:75], v[182:185], v[226:229], v[72:75]
	v_mfma_f32_16x16x32_bf16 v[68:71], v[190:193], v[226:229], v[68:71]
	s_barrier
	s_add_i32 s96, s96, s58
	v_lshl_add_u64 v[218:219], s[52:53], 0, v[134:135]
	s_mov_b32 m0, s96
	ds_read_b128 v[194:197], v158 offset:16384
	ds_read_b128 v[198:201], v158 offset:17408
	ds_read_b128 v[202:205], v158 offset:18432
	ds_read_b128 v[206:209], v158 offset:19456
	ds_read_b128 v[210:213], v158 offset:20480
	ds_read_b128 v[214:217], v158 offset:21504
	ds_read_b128 v[222:225], v158 offset:22528
	ds_read_b128 v[226:229], v158 offset:23552
	global_load_lds_dwordx4 v[218:219], off
	s_add_i32 m0, s96, 0x2000
	s_add_u32 s96, s52, 0x80000
	v_lshl_add_u64 v[230:231], s[52:53], 0, v[138:139]
	s_addc_u32 s97, s53, 0
	s_add_i32 vcc_lo, s85, s58
	global_load_lds_dwordx4 v[230:231], off
	v_lshl_add_u64 v[2:3], s[96:97], 0, v[134:135]
	s_mov_b32 m0, vcc_lo
	v_lshl_add_u64 v[232:233], s[54:55], 0, v[132:133]
	global_load_lds_dwordx4 v[2:3], off
	v_lshl_add_u64 v[2:3], s[96:97], 0, v[138:139]
	s_add_i32 m0, vcc_lo, 0x2000
	v_lshl_add_u64 v[234:235], s[54:55], 0, v[136:137]
	global_load_lds_dwordx4 v[2:3], off
	s_mov_b32 m0, s59
	s_nop 0
	global_load_lds_dwordx4 v[232:233], off
	s_mov_b32 m0, s60
	s_nop 0
	global_load_lds_dwordx4 v[234:235], off
	s_waitcnt vmcnt(8)
	s_waitcnt lgkmcnt(0)
	s_barrier
; #define PG8_STAGE(bufoff, gbase, voff) do { _Pragma("unroll") for (int _i = 0; _i < 2; ++_i) \
;         __builtin_amdgcn_global_load_lds((const unsigned*)((const char*)(gbase) + (voff)[_i]), (PG8_LAS unsigned*)(lds + (bufoff) + ldsw + _i * 8192), 16, 0, 0); } while (0)
; #define PG8_LDA(dst, b, h) do { _Pragma("unroll") for (int m = 0; m < 4; ++m) _Pragma("unroll") for (int k = 0; k < 2; ++k) dst[m][k] = *(const PG8_LAS bf16x8*)(lds + PG8_SA(b, h) + aoff + m * 2048 + k * 1024); } while (0)
; #define PG8_LDB(dst, b, h) do { _Pragma("unroll") for (int n = 0; n < 2; ++n) _Pragma("unroll") for (int k = 0; k < 2; ++k) dst[n][k] = *(const PG8_LAS bf16x8*)(lds + PG8_SB(b, h) + boff + n * 2048 + k * 1024); } while (0)
; #define PG8_MMA(ai, bj, At, Bt) do { __builtin_amdgcn_s_setprio(1); _Pragma("unroll") for (int m = 0; m < 4; ++m) _Pragma("unroll") for (int n = 0; n < 2; ++n) _Pragma("unroll") for (int k = 0; k < 2; ++k) \
;         acc[ai][bj][m][n] = __builtin_amdgcn_mfma_f32_16x16x32_bf16(Bt[n][k], At[m][k], acc[ai][bj][m][n], 0, 0, 0); __builtin_amdgcn_s_setprio(0); } while (0)
; #define PG8_WAIT_V(n) asm volatile("s_waitcnt vmcnt(" #n ")" ::: "memory")
; #define PG8_WAIT_L(n) asm volatile("s_waitcnt lgkmcnt(" #n ")" ::: "memory")
; #define PG8_BAR __builtin_amdgcn_s_barrier()
; #define PG8_SCHED __builtin_amdgcn_sched_barrier(0)
; template <class Epi, class Sched, bool ALIGN_EPI = false, bool SP2 = false>
; __device__ __forceinline__ void gemm_phase(PG8_LAS unsigned char* lds, const Gemm g, const Sched& S, const Epi& E) {
;     ...
;             PG8_WAIT_V(8); PG8_WAIT_L(0); PG8_BAR; PG8_MMA(1, 0, At, B0); PG8_MMA(1, 1, At, B1); PG8_BAR; PG8_SCHED;
;             PG8_LDB(B0, 1, 0); PG8_LDB(B1, 1, 1); PG8_SCHED; PG8_LDA(At, 1, 0); PG8_STAGE(PG8_SA(0, 1), a2 + hstep, voffA);
;             PG8_WAIT_V(8); PG8_WAIT_L(0); PG8_BAR; PG8_MMA(0, 0, At, B0); PG8_MMA(0, 1, At, B1); PG8_BAR; PG8_SCHED;
	s_waitcnt lgkmcnt(0)
	v_mfma_f32_16x16x32_bf16 v[64:67], v[162:165], v[194:197], v[64:67]
	v_mfma_f32_16x16x32_bf16 v[60:63], v[170:173], v[194:197], v[60:63]
	v_mfma_f32_16x16x32_bf16 v[48:51], v[162:165], v[202:205], v[48:51]
	v_mfma_f32_16x16x32_bf16 v[44:47], v[170:173], v[202:205], v[44:47]
	v_mfma_f32_16x16x32_bf16 v[32:35], v[162:165], v[210:213], v[32:35]
	v_mfma_f32_16x16x32_bf16 v[28:31], v[170:173], v[210:213], v[28:31]
	v_mfma_f32_16x16x32_bf16 v[16:19], v[162:165], v[222:225], v[16:19]
	v_mfma_f32_16x16x32_bf16 v[12:15], v[170:173], v[222:225], v[12:15]
	v_mfma_f32_16x16x32_bf16 v[64:67], v[166:169], v[198:201], v[64:67]
	v_mfma_f32_16x16x32_bf16 v[60:63], v[174:177], v[198:201], v[60:63]
	v_mfma_f32_16x16x32_bf16 v[48:51], v[166:169], v[206:209], v[48:51]
	v_mfma_f32_16x16x32_bf16 v[44:47], v[174:177], v[206:209], v[44:47]
	v_mfma_f32_16x16x32_bf16 v[32:35], v[166:169], v[214:217], v[32:35]
	v_mfma_f32_16x16x32_bf16 v[28:31], v[174:177], v[214:217], v[28:31]
	v_mfma_f32_16x16x32_bf16 v[16:19], v[166:169], v[226:229], v[16:19]
	v_mfma_f32_16x16x32_bf16 v[12:15], v[174:177], v[226:229], v[12:15]
	v_mfma_f32_16x16x32_bf16 v[56:59], v[178:181], v[194:197], v[56:59]
	v_mfma_f32_16x16x32_bf16 v[52:55], v[186:189], v[194:197], v[52:55]
	v_mfma_f32_16x16x32_bf16 v[40:43], v[178:181], v[202:205], v[40:43]
	v_mfma_f32_16x16x32_bf16 v[36:39], v[186:189], v[202:205], v[36:39]
	v_mfma_f32_16x16x32_bf16 v[24:27], v[178:181], v[210:213], v[24:27]
	v_mfma_f32_16x16x32_bf16 v[20:23], v[186:189], v[210:213], v[20:23]
	v_mfma_f32_16x16x32_bf16 v[8:11], v[178:181], v[222:225], v[8:11]
	v_mfma_f32_16x16x32_bf16 v[2:5], v[186:189], v[222:225], v[4:7]
	v_mfma_f32_16x16x32_bf16 v[56:59], v[182:185], v[198:201], v[56:59]
	v_mfma_f32_16x16x32_bf16 v[52:55], v[190:193], v[198:201], v[52:55]
	v_mfma_f32_16x16x32_bf16 v[40:43], v[182:185], v[206:209], v[40:43]
	v_mfma_f32_16x16x32_bf16 v[36:39], v[190:193], v[206:209], v[36:39]
	v_mfma_f32_16x16x32_bf16 v[24:27], v[182:185], v[214:217], v[24:27]
	v_mfma_f32_16x16x32_bf16 v[20:23], v[190:193], v[214:217], v[20:23]
	v_mfma_f32_16x16x32_bf16 v[8:11], v[182:185], v[226:229], v[8:11]
	v_mfma_f32_16x16x32_bf16 v[2:5], v[190:193], v[226:229], v[2:5]
	s_barrier
	s_add_i32 s96, 0, 0x18000
	v_add_u32_e32 v0, s96, v156
	s_add_i32 s97, 0, 0x1c000
	ds_read_b128 v[162:165], v0
	ds_read_b128 v[166:169], v0 offset:1024
	ds_read_b128 v[170:173], v0 offset:2048
	ds_read_b128 v[174:177], v0 offset:3072
	v_add_u32_e32 v0, s97, v156
	ds_read_b128 v[178:181], v0
	ds_read_b128 v[182:185], v0 offset:1024
	ds_read_b128 v[186:189], v0 offset:2048
	ds_read_b128 v[190:193], v0 offset:3072
	s_add_u32 s54, s54, 0x80000
	s_addc_u32 s55, s55, 0
	s_mov_b32 m0, s61
	v_lshl_add_u64 v[6:7], s[54:55], 0, v[132:133]
	ds_read_b128 v[194:197], v158 offset:32768
	ds_read_b128 v[198:201], v158 offset:33792
	ds_read_b128 v[202:205], v158 offset:34816
	ds_read_b128 v[206:209], v158 offset:35840
	ds_read_b128 v[210:213], v158 offset:36864
	ds_read_b128 v[214:217], v158 offset:37888
	ds_read_b128 v[222:225], v158 offset:38912
	ds_read_b128 v[226:229], v158 offset:39936
	global_load_lds_dwordx4 v[6:7], off
	v_lshl_add_u64 v[6:7], s[54:55], 0, v[136:137]
	s_mov_b32 m0, s62
	s_nop 0
	global_load_lds_dwordx4 v[6:7], off
	s_waitcnt vmcnt(8)
	s_waitcnt lgkmcnt(0)
	s_barrier
	s_waitcnt lgkmcnt(0)
	v_mfma_f32_16x16x32_bf16 v[128:131], v[162:165], v[194:197], v[128:131]
	v_mfma_f32_16x16x32_bf16 v[124:127], v[170:173], v[194:197], v[124:127]
	v_mfma_f32_16x16x32_bf16 v[112:115], v[162:165], v[202:205], v[112:115]
	v_mfma_f32_16x16x32_bf16 v[108:111], v[170:173], v[202:205], v[108:111]
	v_mfma_f32_16x16x32_bf16 v[96:99], v[162:165], v[210:213], v[96:99]
	v_mfma_f32_16x16x32_bf16 v[92:95], v[170:173], v[210:213], v[92:95]
	v_mfma_f32_16x16x32_bf16 v[80:83], v[162:165], v[222:225], v[80:83]
	v_mfma_f32_16x16x32_bf16 v[76:79], v[170:173], v[222:225], v[76:79]
	v_mfma_f32_16x16x32_bf16 v[128:131], v[166:169], v[198:201], v[128:131]
	v_mfma_f32_16x16x32_bf16 v[124:127], v[174:177], v[198:201], v[124:127]
	v_mfma_f32_16x16x32_bf16 v[112:115], v[166:169], v[206:209], v[112:115]
	v_mfma_f32_16x16x32_bf16 v[108:111], v[174:177], v[206:209], v[108:111]
	v_mfma_f32_16x16x32_bf16 v[96:99], v[166:169], v[214:217], v[96:99]
	v_mfma_f32_16x16x32_bf16 v[92:95], v[174:177], v[214:217], v[92:95]
	v_mfma_f32_16x16x32_bf16 v[80:83], v[166:169], v[226:229], v[80:83]
	v_mfma_f32_16x16x32_bf16 v[76:79], v[174:177], v[226:229], v[76:79]
	v_mfma_f32_16x16x32_bf16 v[120:123], v[178:181], v[194:197], v[120:123]
	v_mfma_f32_16x16x32_bf16 v[116:119], v[186:189], v[194:197], v[116:119]
	v_mfma_f32_16x16x32_bf16 v[104:107], v[178:181], v[202:205], v[104:107]
	v_mfma_f32_16x16x32_bf16 v[100:103], v[186:189], v[202:205], v[100:103]
	v_mfma_f32_16x16x32_bf16 v[88:91], v[178:181], v[210:213], v[88:91]
	v_mfma_f32_16x16x32_bf16 v[84:87], v[186:189], v[210:213], v[84:87]
	v_mfma_f32_16x16x32_bf16 v[72:75], v[178:181], v[222:225], v[72:75]
	v_mfma_f32_16x16x32_bf16 v[68:71], v[186:189], v[222:225], v[68:71]
	v_mfma_f32_16x16x32_bf16 v[120:123], v[182:185], v[198:201], v[120:123]
	v_mfma_f32_16x16x32_bf16 v[116:119], v[190:193], v[198:201], v[116:119]
	v_mfma_f32_16x16x32_bf16 v[104:107], v[182:185], v[206:209], v[104:107]
	v_mfma_f32_16x16x32_bf16 v[100:103], v[190:193], v[206:209], v[100:103]
	v_mfma_f32_16x16x32_bf16 v[88:91], v[182:185], v[214:217], v[88:91]
	v_mfma_f32_16x16x32_bf16 v[84:87], v[190:193], v[214:217], v[84:87]
	v_mfma_f32_16x16x32_bf16 v[72:75], v[182:185], v[226:229], v[72:75]
	v_mfma_f32_16x16x32_bf16 v[68:71], v[190:193], v[226:229], v[68:71]
	s_barrier
; #define PG8_STAGE(bufoff, gbase, voff) do { _Pragma("unroll") for (int _i = 0; _i < 2; ++_i) \
;         __builtin_amdgcn_global_load_lds((const unsigned*)((const char*)(gbase) + (voff)[_i]), (PG8_LAS unsigned*)(lds + (bufoff) + ldsw + _i * 8192), 16, 0, 0); } while (0)
; #define PG8_LDA(dst, b, h) do { _Pragma("unroll") for (int m = 0; m < 4; ++m) _Pragma("unroll") for (int k = 0; k < 2; ++k) dst[m][k] = *(const PG8_LAS bf16x8*)(lds + PG8_SA(b, h) + aoff + m * 2048 + k * 1024); } while (0)
; #define PG8_MMA(ai, bj, At, Bt) do { __builtin_amdgcn_s_setprio(1); _Pragma("unroll") for (int m = 0; m < 4; ++m) _Pragma("unroll") for (int n = 0; n < 2; ++n) _Pragma("unroll") for (int k = 0; k < 2; ++k) \
;         acc[ai][bj][m][n] = __builtin_amdgcn_mfma_f32_16x16x32_bf16(Bt[n][k], At[m][k], acc[ai][bj][m][n], 0, 0, 0); __builtin_amdgcn_s_setprio(0); } while (0)
; #define PG8_WAIT_V(n) asm volatile("s_waitcnt vmcnt(" #n ")" ::: "memory")
; #define PG8_WAIT_L(n) asm volatile("s_waitcnt lgkmcnt(" #n ")" ::: "memory")
; #define PG8_BAR __builtin_amdgcn_s_barrier()
; #define PG8_SCHED __builtin_amdgcn_sched_barrier(0)
; template <class Epi, class Sched, bool ALIGN_EPI = false, bool SP2 = false>
; __device__ __forceinline__ void gemm_phase(PG8_LAS unsigned char* lds, const Gemm g, const Sched& S, const Epi& E) {
;     ...
;         for (int t = 0; t < nt; t += 2) {
;     ...
;             PG8_LDA(At, 1, 1); PG8_STAGE(PG8_SB(1, 0), b3, voffB); PG8_STAGE(PG8_SB(1, 1), b3 + hstep, voffB); PG8_STAGE(PG8_SA(1, 0), a3, voffA);
;             PG8_WAIT_V(8); PG8_WAIT_L(0); PG8_BAR; PG8_MMA(1, 0, At, B0); PG8_MMA(1, 1, At, B1); PG8_BAR; PG8_SCHED;
	s_add_i32 s54, s96, s58
	v_lshl_add_u64 v[6:7], v[218:219], 0, s[8:9]
	s_mov_b32 m0, s54
	ds_read_b128 v[194:197], v158 offset:49152
	ds_read_b128 v[198:201], v158 offset:50176
	ds_read_b128 v[202:205], v158 offset:51200
	ds_read_b128 v[206:209], v158 offset:52224
	ds_read_b128 v[210:213], v158 offset:53248
	ds_read_b128 v[214:217], v158 offset:54272
	ds_read_b128 v[222:225], v158 offset:55296
	ds_read_b128 v[226:229], v158 offset:56320
	global_load_lds_dwordx4 v[6:7], off
	s_add_i32 m0, s54, 0x2000
	s_add_u32 s52, s52, 0x80080
	v_lshl_add_u64 v[6:7], v[230:231], 0, s[8:9]
	s_addc_u32 s53, s53, 0
	s_add_i32 s54, s97, s58
	global_load_lds_dwordx4 v[6:7], off
	v_lshl_add_u64 v[6:7], s[52:53], 0, v[134:135]
	s_mov_b32 m0, s54
	s_nop 0
	global_load_lds_dwordx4 v[6:7], off
	v_lshl_add_u64 v[6:7], s[52:53], 0, v[138:139]
	s_add_i32 m0, s54, 0x2000
	s_nop 0
	global_load_lds_dwordx4 v[6:7], off
	v_lshl_add_u64 v[6:7], v[232:233], 0, s[8:9]
	s_mov_b32 m0, s68
	s_nop 0
	global_load_lds_dwordx4 v[6:7], off
	v_lshl_add_u64 v[6:7], v[234:235], 0, s[8:9]
	s_mov_b32 m0, s69
	s_nop 0
	global_load_lds_dwordx4 v[6:7], off
	s_waitcnt vmcnt(8)
	s_waitcnt lgkmcnt(0)
	s_barrier
	s_waitcnt lgkmcnt(0)
	v_mfma_f32_16x16x32_bf16 v[64:67], v[162:165], v[194:197], v[64:67]
	v_mfma_f32_16x16x32_bf16 v[60:63], v[170:173], v[194:197], v[60:63]
	v_mfma_f32_16x16x32_bf16 v[48:51], v[162:165], v[202:205], v[48:51]
	v_mfma_f32_16x16x32_bf16 v[44:47], v[170:173], v[202:205], v[44:47]
	v_mfma_f32_16x16x32_bf16 v[32:35], v[162:165], v[210:213], v[32:35]
	v_mfma_f32_16x16x32_bf16 v[28:31], v[170:173], v[210:213], v[28:31]
	v_mfma_f32_16x16x32_bf16 v[16:19], v[162:165], v[222:225], v[16:19]
	v_mfma_f32_16x16x32_bf16 v[12:15], v[170:173], v[222:225], v[12:15]
	v_mfma_f32_16x16x32_bf16 v[64:67], v[166:169], v[198:201], v[64:67]
	v_mfma_f32_16x16x32_bf16 v[60:63], v[174:177], v[198:201], v[60:63]
	v_mfma_f32_16x16x32_bf16 v[48:51], v[166:169], v[206:209], v[48:51]
	v_mfma_f32_16x16x32_bf16 v[44:47], v[174:177], v[206:209], v[44:47]
	v_mfma_f32_16x16x32_bf16 v[32:35], v[166:169], v[214:217], v[32:35]
	v_mfma_f32_16x16x32_bf16 v[28:31], v[174:177], v[214:217], v[28:31]
	v_mfma_f32_16x16x32_bf16 v[16:19], v[166:169], v[226:229], v[16:19]
	v_mfma_f32_16x16x32_bf16 v[12:15], v[174:177], v[226:229], v[12:15]
	v_mfma_f32_16x16x32_bf16 v[56:59], v[178:181], v[194:197], v[56:59]
	v_mfma_f32_16x16x32_bf16 v[52:55], v[186:189], v[194:197], v[52:55]
	v_mfma_f32_16x16x32_bf16 v[40:43], v[178:181], v[202:205], v[40:43]
	v_mfma_f32_16x16x32_bf16 v[36:39], v[186:189], v[202:205], v[36:39]
	v_mfma_f32_16x16x32_bf16 v[24:27], v[178:181], v[210:213], v[24:27]
	v_mfma_f32_16x16x32_bf16 v[20:23], v[186:189], v[210:213], v[20:23]
	v_mfma_f32_16x16x32_bf16 v[6:9], v[178:181], v[222:225], v[8:11]
	v_mfma_f32_16x16x32_bf16 v[2:5], v[186:189], v[222:225], v[2:5]
	v_mfma_f32_16x16x32_bf16 v[56:59], v[182:185], v[198:201], v[56:59]
	v_mfma_f32_16x16x32_bf16 v[52:55], v[190:193], v[198:201], v[52:55]
	v_mfma_f32_16x16x32_bf16 v[40:43], v[182:185], v[206:209], v[40:43]
	v_mfma_f32_16x16x32_bf16 v[36:39], v[190:193], v[206:209], v[36:39]
	v_mfma_f32_16x16x32_bf16 v[24:27], v[182:185], v[214:217], v[24:27]
	v_mfma_f32_16x16x32_bf16 v[20:23], v[190:193], v[214:217], v[20:23]
	v_mfma_f32_16x16x32_bf16 v[8:11], v[182:185], v[226:229], v[6:9]
	v_mfma_f32_16x16x32_bf16 v[4:7], v[190:193], v[226:229], v[2:5]
	s_barrier
	s_add_i32 s95, s95, 2
	s_add_u32 s50, s50, 0x100
	s_addc_u32 s51, s51, 0
	s_cmp_gt_u32 s95, 29
	s_cbranch_scc1 .LBB0_630

; __device__ __forceinline__ unsigned cvt_pk_bf16(float lo, float hi) { unsigned r; asm volatile("v_cvt_pk_bf16_f32 %0, %1, %2" : "=v"(r) : "v"(lo), "v"(hi)); return r; }
; __device__ __forceinline__ float bflo(unsigned w) { return __uint_as_float(w << 16); }
; __device__ __forceinline__ float bfhi(unsigned w) { return __uint_as_float(w & 0xffff0000u); }
; __device__ __forceinline__ float sigmoidf_(float x) { return __builtin_amdgcn_rcpf(1.f + __expf(-x)); }
;     static __device__ __forceinline__ float cl(float x) { return fminf(fmaxf(x, -30.f), 30.f); }
;     __device__ __forceinline__ void operator()(const f32x4 (&acc)[2][2][4][2], const Unit& u, int wr, int wc, int fr, int fq) const {
;         const int row0 = u.pm * BM + wr * 64 + fr;
; #pragma unroll
;         for (int ai = 0; ai < 2; ++ai)
; #pragma unroll
;             for (int m = 0; m < 4; ++m) { const size_t row = (size_t)(row0 + ai * HALF + m * 16);
; #pragma unroll
;                 for (int bj = 0; bj < 2; ++bj) { const int col = u.pn * BM + bj * HALF + wc * 32 + 8 * fq;
;                     const u32x4 gw = *(const u32x4*)(gate + (size_t)(2 + (col >> 10)) * SEC + row * 1024 + (col & 1023));
;                     const f32x4 v0 = acc[ai][bj][m][0], v1 = acc[ai][bj][m][1];
;                     float r[8];
;                     r[0] = v0[0] * sigmoidf_(cl(bflo(gw.x))); r[1] = v0[1] * sigmoidf_(cl(bfhi(gw.x))); r[2] = v0[2] * sigmoidf_(cl(bflo(gw.y))); r[3] = v0[3] * sigmoidf_(cl(bfhi(gw.y)));
;                     r[4] = v1[0] * sigmoidf_(cl(bflo(gw.z))); r[5] = v1[1] * sigmoidf_(cl(bfhi(gw.z))); r[6] = v1[2] * sigmoidf_(cl(bflo(gw.w))); r[7] = v1[3] * sigmoidf_(cl(bfhi(gw.w)));
;                     u32x4 w; w.x = cvt_pk_bf16(r[0], r[1]); w.y = cvt_pk_bf16(r[2], r[3]); w.z = cvt_pk_bf16(r[4], r[5]); w.w = cvt_pk_bf16(r[6], r[7]);
;                     *(u32x4*)(mix + row * 2048 + col) = w; } }
.LBB0_632:
	s_lshl_b64 s[46:47], s[48:49], 26
	s_add_u32 s41, s65, s46
	v_add_u32_e32 v150, s89, v155
	s_addc_u32 s47, s66, s47
	v_ashrrev_i32_e32 v151, 31, v150
	s_add_u32 s46, s41, 0x8000000
	v_mov_b32_e32 v0, s31
	v_lshlrev_b64 v[2:3], 11, v[150:151]
	s_addc_u32 s47, s47, 0
	v_bitop3_b32 v0, v157, s86, v0 bitop3:0xc8
	v_lshl_add_u64 v[152:153], s[46:47], 0, v[2:3]
	v_lshlrev_b32_e32 v0, 1, v0
	v_lshl_add_u64 v[2:3], v[152:153], 0, v[0:1]
	global_load_dwordx4 v[162:165], v[2:3], off
	v_lshlrev_b64 v[166:167], 12, v[150:151]
	v_or_b32_e32 v148, s31, v157
	v_ashrrev_i32_e32 v149, 31, v148
	v_bitop3_b32 v2, v148, s87, v160 bitop3:0xc8
	v_lshlrev_b64 v[148:149], 1, v[148:149]
	v_lshl_add_u64 v[166:167], s[38:39], 0, v[166:167]
	v_mov_b32_e32 v3, v1
	v_lshlrev_b32_e32 v2, 1, v2
	v_lshl_add_u64 v[166:167], v[166:167], 0, v[148:149]
	v_lshl_add_u64 v[152:153], v[152:153], 0, v[2:3]
	s_andn2_b64 vcc, exec, s[0:1]
	s_mov_b64 s[0:1], -1
	s_waitcnt vmcnt(0)
	v_lshlrev_b32_e32 v169, 16, v165
	v_and_b32_e32 v165, 0xffff0000, v165
	v_lshlrev_b32_e32 v151, 16, v162
	v_and_b32_e32 v161, 0xffff0000, v162
	v_lshlrev_b32_e32 v162, 16, v163
	v_and_b32_e32 v163, 0xffff0000, v163
	v_lshlrev_b32_e32 v168, 16, v164
	v_and_b32_e32 v164, 0xffff0000, v164
	v_max_f32_e32 v165, v165, v165
	v_max_f32_e32 v151, v151, v151
	v_max_f32_e32 v161, v161, v161
	v_max_f32_e32 v162, v162, v162
	v_max_f32_e32 v163, v163, v163
	v_max_f32_e32 v168, v168, v168
	v_max_f32_e32 v164, v164, v164
	v_max_f32_e32 v169, v169, v169
	v_med3_f32 v165, v165, s73, v159
	v_med3_f32 v151, v151, s73, v159
	v_med3_f32 v161, v161, s73, v159
	v_med3_f32 v162, v162, s73, v159
	v_med3_f32 v163, v163, s73, v159
	v_med3_f32 v168, v168, s73, v159
	v_med3_f32 v164, v164, s73, v159
	v_med3_f32 v169, v169, s73, v159
	v_mul_f32_e32 v165, 0xbfb8aa3b, v165
	v_mul_f32_e32 v151, 0xbfb8aa3b, v151
	v_mul_f32_e32 v161, 0xbfb8aa3b, v161
	v_mul_f32_e32 v162, 0xbfb8aa3b, v162
	v_mul_f32_e32 v163, 0xbfb8aa3b, v163
	v_mul_f32_e32 v168, 0xbfb8aa3b, v168
	v_mul_f32_e32 v164, 0xbfb8aa3b, v164
	v_mul_f32_e32 v169, 0xbfb8aa3b, v169
	v_exp_f32_e32 v165, v165
	v_exp_f32_e32 v151, v151
	v_exp_f32_e32 v161, v161
	v_exp_f32_e32 v162, v162
	v_exp_f32_e32 v163, v163
	v_exp_f32_e32 v168, v168
	v_exp_f32_e32 v164, v164
	v_exp_f32_e32 v169, v169
	v_add_f32_e32 v165, 1.0, v165
	v_add_f32_e32 v151, 1.0, v151
	v_add_f32_e32 v161, 1.0, v161
	v_add_f32_e32 v162, 1.0, v162
	v_add_f32_e32 v163, 1.0, v163
	v_add_f32_e32 v168, 1.0, v168
	v_add_f32_e32 v164, 1.0, v164
	v_add_f32_e32 v169, 1.0, v169
	v_rcp_f32_e32 v165, v165
	v_rcp_f32_e32 v151, v151
	v_rcp_f32_e32 v161, v161
	v_rcp_f32_e32 v162, v162
	v_rcp_f32_e32 v163, v163
	v_rcp_f32_e32 v168, v168
	v_rcp_f32_e32 v164, v164
	v_rcp_f32_e32 v169, v169
	v_mul_f32_e32 v127, v127, v165
	v_mul_f32_e32 v128, v128, v151
	v_mul_f32_e32 v129, v129, v161
	v_mul_f32_e32 v130, v130, v162
	v_mul_f32_e32 v131, v131, v163
	v_mul_f32_e32 v151, v124, v168
	v_mul_f32_e32 v161, v125, v164
	v_mul_f32_e32 v162, v126, v169
	v_cvt_pk_bf16_f32 v124, v128, v129
	v_cvt_pk_bf16_f32 v125, v130, v131
	v_cvt_pk_bf16_f32 v126, v151, v161
	v_cvt_pk_bf16_f32 v127, v162, v127
	global_store_dwordx4 v[166:167], v[124:127], off
	global_load_dwordx4 v[124:127], v[152:153], off
	v_or_b32_e32 v128, 16, v150
	v_ashrrev_i32_e32 v129, 31, v128
	v_lshlrev_b64 v[130:131], 11, v[128:129]
	v_lshl_add_u64 v[130:131], s[46:47], 0, v[130:131]
	v_lshl_add_u64 v[152:153], v[130:131], 0, v[0:1]
	s_waitcnt vmcnt(0)
	v_lshlrev_b32_e32 v163, 16, v127
	v_and_b32_e32 v127, 0xffff0000, v127
	v_lshlrev_b32_e32 v151, 16, v124
	v_and_b32_e32 v124, 0xffff0000, v124
	v_lshlrev_b32_e32 v161, 16, v125
	v_and_b32_e32 v125, 0xffff0000, v125
	v_lshlrev_b32_e32 v162, 16, v126
	v_and_b32_e32 v126, 0xffff0000, v126
	v_max_f32_e32 v127, v127, v127
	v_max_f32_e32 v151, v151, v151
	v_max_f32_e32 v124, v124, v124
	v_max_f32_e32 v161, v161, v161
	v_max_f32_e32 v125, v125, v125
	v_max_f32_e32 v162, v162, v162
	v_max_f32_e32 v126, v126, v126
	v_max_f32_e32 v163, v163, v163
	v_med3_f32 v127, v127, s73, v159
	v_med3_f32 v151, v151, s73, v159
	v_med3_f32 v124, v124, s73, v159
	v_med3_f32 v161, v161, s73, v159
	v_med3_f32 v125, v125, s73, v159
	v_med3_f32 v162, v162, s73, v159
	v_med3_f32 v126, v126, s73, v159
	v_med3_f32 v163, v163, s73, v159
	v_mul_f32_e32 v127, 0xbfb8aa3b, v127
	v_mul_f32_e32 v151, 0xbfb8aa3b, v151
	v_mul_f32_e32 v124, 0xbfb8aa3b, v124
	v_mul_f32_e32 v161, 0xbfb8aa3b, v161
	v_mul_f32_e32 v125, 0xbfb8aa3b, v125
	v_mul_f32_e32 v162, 0xbfb8aa3b, v162
	v_mul_f32_e32 v126, 0xbfb8aa3b, v126
	v_mul_f32_e32 v163, 0xbfb8aa3b, v163
	v_exp_f32_e32 v127, v127
	v_exp_f32_e32 v151, v151
	v_exp_f32_e32 v124, v124
	v_exp_f32_e32 v161, v161
	v_exp_f32_e32 v125, v125
	v_exp_f32_e32 v162, v162
	v_exp_f32_e32 v126, v126
	v_exp_f32_e32 v163, v163
	v_add_f32_e32 v127, 1.0, v127
	v_add_f32_e32 v151, 1.0, v151
	v_add_f32_e32 v124, 1.0, v124
	v_add_f32_e32 v161, 1.0, v161
	v_add_f32_e32 v125, 1.0, v125
	v_add_f32_e32 v162, 1.0, v162
	v_add_f32_e32 v126, 1.0, v126
	v_add_f32_e32 v163, 1.0, v163
	v_rcp_f32_e32 v127, v127
	v_rcp_f32_e32 v151, v151
	v_rcp_f32_e32 v124, v124
	v_rcp_f32_e32 v161, v161
	v_rcp_f32_e32 v125, v125
	v_rcp_f32_e32 v162, v162
	v_rcp_f32_e32 v126, v126
	v_rcp_f32_e32 v163, v163
	v_mul_f32_e32 v119, v119, v127
	v_mul_f32_e32 v120, v120, v151
	v_mul_f32_e32 v121, v121, v124
	v_mul_f32_e32 v122, v122, v161
	v_mul_f32_e32 v123, v123, v125
	v_mul_f32_e32 v124, v116, v162
	v_mul_f32_e32 v125, v117, v126
	v_mul_f32_e32 v126, v118, v163
	v_cvt_pk_bf16_f32 v116, v120, v121
	v_cvt_pk_bf16_f32 v117, v122, v123
	v_cvt_pk_bf16_f32 v118, v124, v125
	v_cvt_pk_bf16_f32 v119, v126, v119
	global_store_dwordx4 v[166:167], v[116:119], off offset:256
	global_load_dwordx4 v[116:119], v[152:153], off
	v_lshlrev_b64 v[120:121], 12, v[128:129]
	v_lshl_add_u64 v[120:121], s[38:39], 0, v[120:121]
	v_lshl_add_u64 v[120:121], v[120:121], 0, v[148:149]
	v_lshl_add_u64 v[122:123], v[130:131], 0, v[2:3]
	s_waitcnt vmcnt(0)
; __device__ __forceinline__ unsigned cvt_pk_bf16(float lo, float hi) { unsigned r; asm volatile("v_cvt_pk_bf16_f32 %0, %1, %2" : "=v"(r) : "v"(lo), "v"(hi)); return r; }
; __device__ __forceinline__ float bflo(unsigned w) { return __uint_as_float(w << 16); }
; __device__ __forceinline__ float bfhi(unsigned w) { return __uint_as_float(w & 0xffff0000u); }
; __device__ __forceinline__ float sigmoidf_(float x) { return __builtin_amdgcn_rcpf(1.f + __expf(-x)); }
;     static __device__ __forceinline__ float cl(float x) { return fminf(fmaxf(x, -30.f), 30.f); }
;     __device__ __forceinline__ void operator()(const f32x4 (&acc)[2][2][4][2], const Unit& u, int wr, int wc, int fr, int fq) const {
;     ...
;             for (int m = 0; m < 4; ++m) { const size_t row = (size_t)(row0 + ai * HALF + m * 16);
; #pragma unroll
;                 for (int bj = 0; bj < 2; ++bj) { const int col = u.pn * BM + bj * HALF + wc * 32 + 8 * fq;
;                     const u32x4 gw = *(const u32x4*)(gate + (size_t)(2 + (col >> 10)) * SEC + row * 1024 + (col & 1023));
;                     const f32x4 v0 = acc[ai][bj][m][0], v1 = acc[ai][bj][m][1];
;                     float r[8];
;                     r[0] = v0[0] * sigmoidf_(cl(bflo(gw.x))); r[1] = v0[1] * sigmoidf_(cl(bfhi(gw.x))); r[2] = v0[2] * sigmoidf_(cl(bflo(gw.y))); r[3] = v0[3] * sigmoidf_(cl(bfhi(gw.y)));
;                     r[4] = v1[0] * sigmoidf_(cl(bflo(gw.z))); r[5] = v1[1] * sigmoidf_(cl(bfhi(gw.z))); r[6] = v1[2] * sigmoidf_(cl(bflo(gw.w))); r[7] = v1[3] * sigmoidf_(cl(bfhi(gw.w)));
;                     u32x4 w; w.x = cvt_pk_bf16(r[0], r[1]); w.y = cvt_pk_bf16(r[2], r[3]); w.z = cvt_pk_bf16(r[4], r[5]); w.w = cvt_pk_bf16(r[6], r[7]);
;                     *(u32x4*)(mix + row * 2048 + col) = w; } }
	v_lshlrev_b32_e32 v127, 16, v119
	v_and_b32_e32 v119, 0xffff0000, v119
	v_lshlrev_b32_e32 v124, 16, v116
	v_and_b32_e32 v116, 0xffff0000, v116
	v_lshlrev_b32_e32 v125, 16, v117
	v_and_b32_e32 v117, 0xffff0000, v117
	v_lshlrev_b32_e32 v126, 16, v118
	v_and_b32_e32 v118, 0xffff0000, v118
	v_max_f32_e32 v119, v119, v119
	v_max_f32_e32 v124, v124, v124
	v_max_f32_e32 v116, v116, v116
	v_max_f32_e32 v125, v125, v125
	v_max_f32_e32 v117, v117, v117
	v_max_f32_e32 v126, v126, v126
	v_max_f32_e32 v118, v118, v118
	v_max_f32_e32 v127, v127, v127
	v_med3_f32 v119, v119, s73, v159
	v_med3_f32 v124, v124, s73, v159
	v_med3_f32 v116, v116, s73, v159
	v_med3_f32 v125, v125, s73, v159
	v_med3_f32 v117, v117, s73, v159
	v_med3_f32 v126, v126, s73, v159
	v_med3_f32 v118, v118, s73, v159
	v_med3_f32 v127, v127, s73, v159
	v_mul_f32_e32 v119, 0xbfb8aa3b, v119
	v_mul_f32_e32 v124, 0xbfb8aa3b, v124
	v_mul_f32_e32 v116, 0xbfb8aa3b, v116
	v_mul_f32_e32 v125, 0xbfb8aa3b, v125
	v_mul_f32_e32 v117, 0xbfb8aa3b, v117
	v_mul_f32_e32 v126, 0xbfb8aa3b, v126
	v_mul_f32_e32 v118, 0xbfb8aa3b, v118
	v_mul_f32_e32 v127, 0xbfb8aa3b, v127
	v_exp_f32_e32 v119, v119
	v_exp_f32_e32 v124, v124
	v_exp_f32_e32 v116, v116
	v_exp_f32_e32 v125, v125
	v_exp_f32_e32 v117, v117
	v_exp_f32_e32 v126, v126
	v_exp_f32_e32 v118, v118
	v_exp_f32_e32 v127, v127
	v_add_f32_e32 v119, 1.0, v119
	v_add_f32_e32 v124, 1.0, v124
	v_add_f32_e32 v116, 1.0, v116
	v_add_f32_e32 v125, 1.0, v125
	v_add_f32_e32 v117, 1.0, v117
	v_add_f32_e32 v126, 1.0, v126
	v_add_f32_e32 v118, 1.0, v118
	v_add_f32_e32 v127, 1.0, v127
	v_rcp_f32_e32 v119, v119
	v_rcp_f32_e32 v124, v124
	v_rcp_f32_e32 v116, v116
	v_rcp_f32_e32 v125, v125
	v_rcp_f32_e32 v117, v117
	v_rcp_f32_e32 v126, v126
	v_rcp_f32_e32 v118, v118
	v_rcp_f32_e32 v127, v127
	v_mul_f32_e32 v111, v111, v119
	v_mul_f32_e32 v112, v112, v124
	v_mul_f32_e32 v113, v113, v116
	v_mul_f32_e32 v114, v114, v125
	v_mul_f32_e32 v115, v115, v117
	v_mul_f32_e32 v116, v108, v126
	v_mul_f32_e32 v117, v109, v118
	v_mul_f32_e32 v118, v110, v127
	v_cvt_pk_bf16_f32 v108, v112, v113
	v_cvt_pk_bf16_f32 v109, v114, v115
	v_cvt_pk_bf16_f32 v110, v116, v117
	v_cvt_pk_bf16_f32 v111, v118, v111
	global_store_dwordx4 v[120:121], v[108:111], off
	global_load_dwordx4 v[108:111], v[122:123], off
	v_or_b32_e32 v112, 32, v150
	v_ashrrev_i32_e32 v113, 31, v112
	v_lshlrev_b64 v[114:115], 11, v[112:113]
	v_lshl_add_u64 v[114:115], s[46:47], 0, v[114:115]
	v_lshl_add_u64 v[116:117], v[114:115], 0, v[0:1]
	s_waitcnt vmcnt(0)
	v_lshlrev_b32_e32 v123, 16, v111
	v_and_b32_e32 v111, 0xffff0000, v111
	v_lshlrev_b32_e32 v118, 16, v108
	v_and_b32_e32 v108, 0xffff0000, v108
	v_lshlrev_b32_e32 v119, 16, v109
	v_and_b32_e32 v109, 0xffff0000, v109
	v_lshlrev_b32_e32 v122, 16, v110
	v_and_b32_e32 v110, 0xffff0000, v110
	v_max_f32_e32 v111, v111, v111
	v_max_f32_e32 v118, v118, v118
	v_max_f32_e32 v108, v108, v108
	v_max_f32_e32 v119, v119, v119
	v_max_f32_e32 v109, v109, v109
	v_max_f32_e32 v122, v122, v122
	v_max_f32_e32 v110, v110, v110
	v_max_f32_e32 v123, v123, v123
	v_med3_f32 v111, v111, s73, v159
	v_med3_f32 v118, v118, s73, v159
	v_med3_f32 v108, v108, s73, v159
	v_med3_f32 v119, v119, s73, v159
	v_med3_f32 v109, v109, s73, v159
	v_med3_f32 v122, v122, s73, v159
	v_med3_f32 v110, v110, s73, v159
	v_med3_f32 v123, v123, s73, v159
	v_mul_f32_e32 v111, 0xbfb8aa3b, v111
	v_mul_f32_e32 v118, 0xbfb8aa3b, v118
	v_mul_f32_e32 v108, 0xbfb8aa3b, v108
	v_mul_f32_e32 v119, 0xbfb8aa3b, v119
	v_mul_f32_e32 v109, 0xbfb8aa3b, v109
	v_mul_f32_e32 v122, 0xbfb8aa3b, v122
	v_mul_f32_e32 v110, 0xbfb8aa3b, v110
	v_mul_f32_e32 v123, 0xbfb8aa3b, v123
	v_exp_f32_e32 v111, v111
	v_exp_f32_e32 v118, v118
	v_exp_f32_e32 v108, v108
	v_exp_f32_e32 v119, v119
	v_exp_f32_e32 v109, v109
	v_exp_f32_e32 v122, v122
	v_exp_f32_e32 v110, v110
	v_exp_f32_e32 v123, v123
	v_add_f32_e32 v111, 1.0, v111
	v_add_f32_e32 v118, 1.0, v118
	v_add_f32_e32 v108, 1.0, v108
	v_add_f32_e32 v119, 1.0, v119
	v_add_f32_e32 v109, 1.0, v109
	v_add_f32_e32 v122, 1.0, v122
	v_add_f32_e32 v110, 1.0, v110
	v_add_f32_e32 v123, 1.0, v123
	v_rcp_f32_e32 v111, v111
	v_rcp_f32_e32 v118, v118
	v_rcp_f32_e32 v108, v108
	v_rcp_f32_e32 v119, v119
	v_rcp_f32_e32 v109, v109
	v_rcp_f32_e32 v122, v122
	v_rcp_f32_e32 v110, v110
	v_rcp_f32_e32 v123, v123
	v_mul_f32_e32 v103, v103, v111
	v_mul_f32_e32 v104, v104, v118
	v_mul_f32_e32 v105, v105, v108
	v_mul_f32_e32 v106, v106, v119
	v_mul_f32_e32 v107, v107, v109
	v_mul_f32_e32 v108, v100, v122
	v_mul_f32_e32 v109, v101, v110
	v_mul_f32_e32 v110, v102, v123
	v_cvt_pk_bf16_f32 v100, v104, v105
	v_cvt_pk_bf16_f32 v101, v106, v107
	v_cvt_pk_bf16_f32 v102, v108, v109
	v_cvt_pk_bf16_f32 v103, v110, v103
	global_store_dwordx4 v[120:121], v[100:103], off offset:256
	global_load_dwordx4 v[100:103], v[116:117], off
	v_lshlrev_b64 v[104:105], 12, v[112:113]
	v_lshl_add_u64 v[104:105], s[38:39], 0, v[104:105]
	v_lshl_add_u64 v[104:105], v[104:105], 0, v[148:149]
	v_lshl_add_u64 v[106:107], v[114:115], 0, v[2:3]
	s_waitcnt vmcnt(0)
; __device__ __forceinline__ unsigned cvt_pk_bf16(float lo, float hi) { unsigned r; asm volatile("v_cvt_pk_bf16_f32 %0, %1, %2" : "=v"(r) : "v"(lo), "v"(hi)); return r; }
; __device__ __forceinline__ float bflo(unsigned w) { return __uint_as_float(w << 16); }
; __device__ __forceinline__ float bfhi(unsigned w) { return __uint_as_float(w & 0xffff0000u); }
; __device__ __forceinline__ float sigmoidf_(float x) { return __builtin_amdgcn_rcpf(1.f + __expf(-x)); }
;     static __device__ __forceinline__ float cl(float x) { return fminf(fmaxf(x, -30.f), 30.f); }
;     __device__ __forceinline__ void operator()(const f32x4 (&acc)[2][2][4][2], const Unit& u, int wr, int wc, int fr, int fq) const {
;     ...
;             for (int m = 0; m < 4; ++m) { const size_t row = (size_t)(row0 + ai * HALF + m * 16);
; #pragma unroll
;                 for (int bj = 0; bj < 2; ++bj) { const int col = u.pn * BM + bj * HALF + wc * 32 + 8 * fq;
;                     const u32x4 gw = *(const u32x4*)(gate + (size_t)(2 + (col >> 10)) * SEC + row * 1024 + (col & 1023));
;                     const f32x4 v0 = acc[ai][bj][m][0], v1 = acc[ai][bj][m][1];
;                     float r[8];
;                     r[0] = v0[0] * sigmoidf_(cl(bflo(gw.x))); r[1] = v0[1] * sigmoidf_(cl(bfhi(gw.x))); r[2] = v0[2] * sigmoidf_(cl(bflo(gw.y))); r[3] = v0[3] * sigmoidf_(cl(bfhi(gw.y)));
;                     r[4] = v1[0] * sigmoidf_(cl(bflo(gw.z))); r[5] = v1[1] * sigmoidf_(cl(bfhi(gw.z))); r[6] = v1[2] * sigmoidf_(cl(bflo(gw.w))); r[7] = v1[3] * sigmoidf_(cl(bfhi(gw.w)));
;                     u32x4 w; w.x = cvt_pk_bf16(r[0], r[1]); w.y = cvt_pk_bf16(r[2], r[3]); w.z = cvt_pk_bf16(r[4], r[5]); w.w = cvt_pk_bf16(r[6], r[7]);
;                     *(u32x4*)(mix + row * 2048 + col) = w; } }
	v_lshlrev_b32_e32 v111, 16, v103
	v_and_b32_e32 v103, 0xffff0000, v103
	v_lshlrev_b32_e32 v108, 16, v100
	v_and_b32_e32 v100, 0xffff0000, v100
	v_lshlrev_b32_e32 v109, 16, v101
	v_and_b32_e32 v101, 0xffff0000, v101
	v_lshlrev_b32_e32 v110, 16, v102
	v_and_b32_e32 v102, 0xffff0000, v102
	v_max_f32_e32 v103, v103, v103
	v_max_f32_e32 v108, v108, v108
	v_max_f32_e32 v100, v100, v100
	v_max_f32_e32 v109, v109, v109
	v_max_f32_e32 v101, v101, v101
	v_max_f32_e32 v110, v110, v110
	v_max_f32_e32 v102, v102, v102
	v_max_f32_e32 v111, v111, v111
	v_med3_f32 v103, v103, s73, v159
	v_med3_f32 v108, v108, s73, v159
	v_med3_f32 v100, v100, s73, v159
	v_med3_f32 v109, v109, s73, v159
	v_med3_f32 v101, v101, s73, v159
	v_med3_f32 v110, v110, s73, v159
	v_med3_f32 v102, v102, s73, v159
	v_med3_f32 v111, v111, s73, v159
	v_mul_f32_e32 v103, 0xbfb8aa3b, v103
	v_mul_f32_e32 v108, 0xbfb8aa3b, v108
	v_mul_f32_e32 v100, 0xbfb8aa3b, v100
	v_mul_f32_e32 v109, 0xbfb8aa3b, v109
	v_mul_f32_e32 v101, 0xbfb8aa3b, v101
	v_mul_f32_e32 v110, 0xbfb8aa3b, v110
	v_mul_f32_e32 v102, 0xbfb8aa3b, v102
	v_mul_f32_e32 v111, 0xbfb8aa3b, v111
	v_exp_f32_e32 v103, v103
	v_exp_f32_e32 v108, v108
	v_exp_f32_e32 v100, v100
	v_exp_f32_e32 v109, v109
	v_exp_f32_e32 v101, v101
	v_exp_f32_e32 v110, v110
	v_exp_f32_e32 v102, v102
	v_exp_f32_e32 v111, v111
	v_add_f32_e32 v103, 1.0, v103
	v_add_f32_e32 v108, 1.0, v108
	v_add_f32_e32 v100, 1.0, v100
	v_add_f32_e32 v109, 1.0, v109
	v_add_f32_e32 v101, 1.0, v101
	v_add_f32_e32 v110, 1.0, v110
	v_add_f32_e32 v102, 1.0, v102
	v_add_f32_e32 v111, 1.0, v111
	v_rcp_f32_e32 v103, v103
	v_rcp_f32_e32 v108, v108
	v_rcp_f32_e32 v100, v100
	v_rcp_f32_e32 v109, v109
	v_rcp_f32_e32 v101, v101
	v_rcp_f32_e32 v110, v110
	v_rcp_f32_e32 v102, v102
	v_rcp_f32_e32 v111, v111
	v_mul_f32_e32 v95, v95, v103
	v_mul_f32_e32 v96, v96, v108
	v_mul_f32_e32 v97, v97, v100
	v_mul_f32_e32 v98, v98, v109
	v_mul_f32_e32 v99, v99, v101
	v_mul_f32_e32 v100, v92, v110
	v_mul_f32_e32 v101, v93, v102
	v_mul_f32_e32 v102, v94, v111
	v_cvt_pk_bf16_f32 v92, v96, v97
	v_cvt_pk_bf16_f32 v93, v98, v99
	v_cvt_pk_bf16_f32 v94, v100, v101
	v_cvt_pk_bf16_f32 v95, v102, v95
	global_store_dwordx4 v[104:105], v[92:95], off
	global_load_dwordx4 v[92:95], v[106:107], off
	v_or_b32_e32 v96, 48, v150
	v_ashrrev_i32_e32 v97, 31, v96
	v_lshlrev_b64 v[98:99], 11, v[96:97]
	v_lshl_add_u64 v[98:99], s[46:47], 0, v[98:99]
	v_lshl_add_u64 v[100:101], v[98:99], 0, v[0:1]
	s_waitcnt vmcnt(0)
	v_lshlrev_b32_e32 v107, 16, v95
	v_and_b32_e32 v95, 0xffff0000, v95
	v_lshlrev_b32_e32 v102, 16, v92
	v_and_b32_e32 v92, 0xffff0000, v92
	v_lshlrev_b32_e32 v103, 16, v93
	v_and_b32_e32 v93, 0xffff0000, v93
	v_lshlrev_b32_e32 v106, 16, v94
	v_and_b32_e32 v94, 0xffff0000, v94
	v_max_f32_e32 v95, v95, v95
	v_max_f32_e32 v102, v102, v102
	v_max_f32_e32 v92, v92, v92
	v_max_f32_e32 v103, v103, v103
	v_max_f32_e32 v93, v93, v93
	v_max_f32_e32 v106, v106, v106
	v_max_f32_e32 v94, v94, v94
	v_max_f32_e32 v107, v107, v107
	v_med3_f32 v95, v95, s73, v159
	v_med3_f32 v102, v102, s73, v159
	v_med3_f32 v92, v92, s73, v159
	v_med3_f32 v103, v103, s73, v159
	v_med3_f32 v93, v93, s73, v159
	v_med3_f32 v106, v106, s73, v159
	v_med3_f32 v94, v94, s73, v159
	v_med3_f32 v107, v107, s73, v159
	v_mul_f32_e32 v95, 0xbfb8aa3b, v95
	v_mul_f32_e32 v102, 0xbfb8aa3b, v102
	v_mul_f32_e32 v92, 0xbfb8aa3b, v92
	v_mul_f32_e32 v103, 0xbfb8aa3b, v103
	v_mul_f32_e32 v93, 0xbfb8aa3b, v93
	v_mul_f32_e32 v106, 0xbfb8aa3b, v106
	v_mul_f32_e32 v94, 0xbfb8aa3b, v94
	v_mul_f32_e32 v107, 0xbfb8aa3b, v107
	v_exp_f32_e32 v95, v95
	v_exp_f32_e32 v102, v102
	v_exp_f32_e32 v92, v92
	v_exp_f32_e32 v103, v103
	v_exp_f32_e32 v93, v93
	v_exp_f32_e32 v106, v106
	v_exp_f32_e32 v94, v94
	v_exp_f32_e32 v107, v107
	v_add_f32_e32 v95, 1.0, v95
	v_add_f32_e32 v102, 1.0, v102
	v_add_f32_e32 v92, 1.0, v92
	v_add_f32_e32 v103, 1.0, v103
	v_add_f32_e32 v93, 1.0, v93
	v_add_f32_e32 v106, 1.0, v106
	v_add_f32_e32 v94, 1.0, v94
	v_add_f32_e32 v107, 1.0, v107
	v_rcp_f32_e32 v95, v95
	v_rcp_f32_e32 v102, v102
	v_rcp_f32_e32 v92, v92
	v_rcp_f32_e32 v103, v103
	v_rcp_f32_e32 v93, v93
	v_rcp_f32_e32 v106, v106
	v_rcp_f32_e32 v94, v94
	v_rcp_f32_e32 v107, v107
	v_mul_f32_e32 v87, v87, v95
	v_mul_f32_e32 v88, v88, v102
	v_mul_f32_e32 v89, v89, v92
	v_mul_f32_e32 v90, v90, v103
	v_mul_f32_e32 v91, v91, v93
	v_mul_f32_e32 v92, v84, v106
	v_mul_f32_e32 v93, v85, v94
	v_mul_f32_e32 v94, v86, v107
	v_cvt_pk_bf16_f32 v84, v88, v89
	v_cvt_pk_bf16_f32 v85, v90, v91
	v_cvt_pk_bf16_f32 v86, v92, v93
	v_cvt_pk_bf16_f32 v87, v94, v87
	global_store_dwordx4 v[104:105], v[84:87], off offset:256
	global_load_dwordx4 v[84:87], v[100:101], off
	v_lshlrev_b64 v[88:89], 12, v[96:97]
	v_lshl_add_u64 v[88:89], s[38:39], 0, v[88:89]
	v_lshl_add_u64 v[88:89], v[88:89], 0, v[148:149]
	v_lshl_add_u64 v[90:91], v[98:99], 0, v[2:3]
	s_waitcnt vmcnt(0)
; __device__ __forceinline__ unsigned cvt_pk_bf16(float lo, float hi) { unsigned r; asm volatile("v_cvt_pk_bf16_f32 %0, %1, %2" : "=v"(r) : "v"(lo), "v"(hi)); return r; }
; __device__ __forceinline__ float bflo(unsigned w) { return __uint_as_float(w << 16); }
; __device__ __forceinline__ float bfhi(unsigned w) { return __uint_as_float(w & 0xffff0000u); }
; __device__ __forceinline__ float sigmoidf_(float x) { return __builtin_amdgcn_rcpf(1.f + __expf(-x)); }
;     static __device__ __forceinline__ float cl(float x) { return fminf(fmaxf(x, -30.f), 30.f); }
;     __device__ __forceinline__ void operator()(const f32x4 (&acc)[2][2][4][2], const Unit& u, int wr, int wc, int fr, int fq) const {
;     ...
;             for (int m = 0; m < 4; ++m) { const size_t row = (size_t)(row0 + ai * HALF + m * 16);
; #pragma unroll
;                 for (int bj = 0; bj < 2; ++bj) { const int col = u.pn * BM + bj * HALF + wc * 32 + 8 * fq;
;                     const u32x4 gw = *(const u32x4*)(gate + (size_t)(2 + (col >> 10)) * SEC + row * 1024 + (col & 1023));
;                     const f32x4 v0 = acc[ai][bj][m][0], v1 = acc[ai][bj][m][1];
;                     float r[8];
;                     r[0] = v0[0] * sigmoidf_(cl(bflo(gw.x))); r[1] = v0[1] * sigmoidf_(cl(bfhi(gw.x))); r[2] = v0[2] * sigmoidf_(cl(bflo(gw.y))); r[3] = v0[3] * sigmoidf_(cl(bfhi(gw.y)));
;                     r[4] = v1[0] * sigmoidf_(cl(bflo(gw.z))); r[5] = v1[1] * sigmoidf_(cl(bfhi(gw.z))); r[6] = v1[2] * sigmoidf_(cl(bflo(gw.w))); r[7] = v1[3] * sigmoidf_(cl(bfhi(gw.w)));
;                     u32x4 w; w.x = cvt_pk_bf16(r[0], r[1]); w.y = cvt_pk_bf16(r[2], r[3]); w.z = cvt_pk_bf16(r[4], r[5]); w.w = cvt_pk_bf16(r[6], r[7]);
;                     *(u32x4*)(mix + row * 2048 + col) = w; } }
	v_lshlrev_b32_e32 v95, 16, v87
	v_and_b32_e32 v87, 0xffff0000, v87
	v_lshlrev_b32_e32 v92, 16, v84
	v_and_b32_e32 v84, 0xffff0000, v84
	v_lshlrev_b32_e32 v93, 16, v85
	v_and_b32_e32 v85, 0xffff0000, v85
	v_lshlrev_b32_e32 v94, 16, v86
	v_and_b32_e32 v86, 0xffff0000, v86
	v_max_f32_e32 v87, v87, v87
	v_max_f32_e32 v92, v92, v92
	v_max_f32_e32 v84, v84, v84
	v_max_f32_e32 v93, v93, v93
	v_max_f32_e32 v85, v85, v85
	v_max_f32_e32 v94, v94, v94
	v_max_f32_e32 v86, v86, v86
	v_max_f32_e32 v95, v95, v95
	v_med3_f32 v87, v87, s73, v159
	v_med3_f32 v92, v92, s73, v159
	v_med3_f32 v84, v84, s73, v159
	v_med3_f32 v93, v93, s73, v159
	v_med3_f32 v85, v85, s73, v159
	v_med3_f32 v94, v94, s73, v159
	v_med3_f32 v86, v86, s73, v159
	v_med3_f32 v95, v95, s73, v159
	v_mul_f32_e32 v87, 0xbfb8aa3b, v87
	v_mul_f32_e32 v92, 0xbfb8aa3b, v92
	v_mul_f32_e32 v84, 0xbfb8aa3b, v84
	v_mul_f32_e32 v93, 0xbfb8aa3b, v93
	v_mul_f32_e32 v85, 0xbfb8aa3b, v85
	v_mul_f32_e32 v94, 0xbfb8aa3b, v94
	v_mul_f32_e32 v86, 0xbfb8aa3b, v86
	v_mul_f32_e32 v95, 0xbfb8aa3b, v95
	v_exp_f32_e32 v87, v87
	v_exp_f32_e32 v92, v92
	v_exp_f32_e32 v84, v84
	v_exp_f32_e32 v93, v93
	v_exp_f32_e32 v85, v85
	v_exp_f32_e32 v94, v94
	v_exp_f32_e32 v86, v86
	v_exp_f32_e32 v95, v95
	v_add_f32_e32 v87, 1.0, v87
	v_add_f32_e32 v92, 1.0, v92
	v_add_f32_e32 v84, 1.0, v84
	v_add_f32_e32 v93, 1.0, v93
	v_add_f32_e32 v85, 1.0, v85
	v_add_f32_e32 v94, 1.0, v94
	v_add_f32_e32 v86, 1.0, v86
	v_add_f32_e32 v95, 1.0, v95
	v_rcp_f32_e32 v87, v87
	v_rcp_f32_e32 v92, v92
	v_rcp_f32_e32 v84, v84
	v_rcp_f32_e32 v93, v93
	v_rcp_f32_e32 v85, v85
	v_rcp_f32_e32 v94, v94
	v_rcp_f32_e32 v86, v86
	v_rcp_f32_e32 v95, v95
	v_mul_f32_e32 v79, v79, v87
	v_mul_f32_e32 v80, v80, v92
	v_mul_f32_e32 v81, v81, v84
	v_mul_f32_e32 v82, v82, v93
	v_mul_f32_e32 v83, v83, v85
	v_mul_f32_e32 v84, v76, v94
	v_mul_f32_e32 v85, v77, v86
	v_mul_f32_e32 v86, v78, v95
	v_cvt_pk_bf16_f32 v76, v80, v81
	v_cvt_pk_bf16_f32 v77, v82, v83
	v_cvt_pk_bf16_f32 v78, v84, v85
	v_cvt_pk_bf16_f32 v79, v86, v79
	global_store_dwordx4 v[88:89], v[76:79], off
	global_load_dwordx4 v[76:79], v[90:91], off
	v_add_u32_e32 v80, 0x80, v150
	v_ashrrev_i32_e32 v81, 31, v80
	v_lshlrev_b64 v[82:83], 11, v[80:81]
	v_lshl_add_u64 v[82:83], s[46:47], 0, v[82:83]
	v_lshl_add_u64 v[84:85], v[82:83], 0, v[0:1]
	s_waitcnt vmcnt(0)
	v_lshlrev_b32_e32 v91, 16, v79
	v_and_b32_e32 v79, 0xffff0000, v79
	v_lshlrev_b32_e32 v86, 16, v76
	v_and_b32_e32 v76, 0xffff0000, v76
	v_lshlrev_b32_e32 v87, 16, v77
	v_and_b32_e32 v77, 0xffff0000, v77
	v_lshlrev_b32_e32 v90, 16, v78
	v_and_b32_e32 v78, 0xffff0000, v78
	v_max_f32_e32 v79, v79, v79
	v_max_f32_e32 v86, v86, v86
	v_max_f32_e32 v76, v76, v76
	v_max_f32_e32 v87, v87, v87
	v_max_f32_e32 v77, v77, v77
	v_max_f32_e32 v90, v90, v90
	v_max_f32_e32 v78, v78, v78
	v_max_f32_e32 v91, v91, v91
	v_med3_f32 v79, v79, s73, v159
	v_med3_f32 v86, v86, s73, v159
	v_med3_f32 v76, v76, s73, v159
	v_med3_f32 v87, v87, s73, v159
	v_med3_f32 v77, v77, s73, v159
	v_med3_f32 v90, v90, s73, v159
	v_med3_f32 v78, v78, s73, v159
	v_med3_f32 v91, v91, s73, v159
	v_mul_f32_e32 v79, 0xbfb8aa3b, v79
	v_mul_f32_e32 v86, 0xbfb8aa3b, v86
	v_mul_f32_e32 v76, 0xbfb8aa3b, v76
	v_mul_f32_e32 v87, 0xbfb8aa3b, v87
	v_mul_f32_e32 v77, 0xbfb8aa3b, v77
	v_mul_f32_e32 v90, 0xbfb8aa3b, v90
	v_mul_f32_e32 v78, 0xbfb8aa3b, v78
	v_mul_f32_e32 v91, 0xbfb8aa3b, v91
	v_exp_f32_e32 v79, v79
	v_exp_f32_e32 v86, v86
	v_exp_f32_e32 v76, v76
	v_exp_f32_e32 v87, v87
	v_exp_f32_e32 v77, v77
	v_exp_f32_e32 v90, v90
	v_exp_f32_e32 v78, v78
	v_exp_f32_e32 v91, v91
	v_add_f32_e32 v79, 1.0, v79
	v_add_f32_e32 v86, 1.0, v86
	v_add_f32_e32 v76, 1.0, v76
	v_add_f32_e32 v87, 1.0, v87
	v_add_f32_e32 v77, 1.0, v77
	v_add_f32_e32 v90, 1.0, v90
	v_add_f32_e32 v78, 1.0, v78
	v_add_f32_e32 v91, 1.0, v91
	v_rcp_f32_e32 v79, v79
	v_rcp_f32_e32 v86, v86
	v_rcp_f32_e32 v76, v76
	v_rcp_f32_e32 v87, v87
	v_rcp_f32_e32 v77, v77
	v_rcp_f32_e32 v90, v90
	v_rcp_f32_e32 v78, v78
	v_rcp_f32_e32 v91, v91
	v_mul_f32_e32 v71, v71, v79
	v_mul_f32_e32 v72, v72, v86
	v_mul_f32_e32 v73, v73, v76
	v_mul_f32_e32 v74, v74, v87
	v_mul_f32_e32 v75, v75, v77
	v_mul_f32_e32 v76, v68, v90
	v_mul_f32_e32 v77, v69, v78
	v_mul_f32_e32 v78, v70, v91
	v_cvt_pk_bf16_f32 v68, v72, v73
	v_cvt_pk_bf16_f32 v69, v74, v75
	v_cvt_pk_bf16_f32 v70, v76, v77
	v_cvt_pk_bf16_f32 v71, v78, v71
	global_store_dwordx4 v[88:89], v[68:71], off offset:256
	global_load_dwordx4 v[68:71], v[84:85], off
	v_lshlrev_b64 v[72:73], 12, v[80:81]
	v_lshl_add_u64 v[72:73], s[38:39], 0, v[72:73]
	v_lshl_add_u64 v[72:73], v[72:73], 0, v[148:149]
	v_lshl_add_u64 v[74:75], v[82:83], 0, v[2:3]
	s_waitcnt vmcnt(0)
; __device__ __forceinline__ unsigned cvt_pk_bf16(float lo, float hi) { unsigned r; asm volatile("v_cvt_pk_bf16_f32 %0, %1, %2" : "=v"(r) : "v"(lo), "v"(hi)); return r; }
; __device__ __forceinline__ float bflo(unsigned w) { return __uint_as_float(w << 16); }
; __device__ __forceinline__ float bfhi(unsigned w) { return __uint_as_float(w & 0xffff0000u); }
; __device__ __forceinline__ float sigmoidf_(float x) { return __builtin_amdgcn_rcpf(1.f + __expf(-x)); }
;     static __device__ __forceinline__ float cl(float x) { return fminf(fmaxf(x, -30.f), 30.f); }
;     __device__ __forceinline__ void operator()(const f32x4 (&acc)[2][2][4][2], const Unit& u, int wr, int wc, int fr, int fq) const {
;     ...
;             for (int m = 0; m < 4; ++m) { const size_t row = (size_t)(row0 + ai * HALF + m * 16);
; #pragma unroll
;                 for (int bj = 0; bj < 2; ++bj) { const int col = u.pn * BM + bj * HALF + wc * 32 + 8 * fq;
;                     const u32x4 gw = *(const u32x4*)(gate + (size_t)(2 + (col >> 10)) * SEC + row * 1024 + (col & 1023));
;                     const f32x4 v0 = acc[ai][bj][m][0], v1 = acc[ai][bj][m][1];
;                     float r[8];
;                     r[0] = v0[0] * sigmoidf_(cl(bflo(gw.x))); r[1] = v0[1] * sigmoidf_(cl(bfhi(gw.x))); r[2] = v0[2] * sigmoidf_(cl(bflo(gw.y))); r[3] = v0[3] * sigmoidf_(cl(bfhi(gw.y)));
;                     r[4] = v1[0] * sigmoidf_(cl(bflo(gw.z))); r[5] = v1[1] * sigmoidf_(cl(bfhi(gw.z))); r[6] = v1[2] * sigmoidf_(cl(bflo(gw.w))); r[7] = v1[3] * sigmoidf_(cl(bfhi(gw.w)));
;                     u32x4 w; w.x = cvt_pk_bf16(r[0], r[1]); w.y = cvt_pk_bf16(r[2], r[3]); w.z = cvt_pk_bf16(r[4], r[5]); w.w = cvt_pk_bf16(r[6], r[7]);
;                     *(u32x4*)(mix + row * 2048 + col) = w; } }
	v_lshlrev_b32_e32 v79, 16, v71
	v_and_b32_e32 v71, 0xffff0000, v71
	v_lshlrev_b32_e32 v76, 16, v68
	v_and_b32_e32 v68, 0xffff0000, v68
	v_lshlrev_b32_e32 v77, 16, v69
	v_and_b32_e32 v69, 0xffff0000, v69
	v_lshlrev_b32_e32 v78, 16, v70
	v_and_b32_e32 v70, 0xffff0000, v70
	v_max_f32_e32 v71, v71, v71
	v_max_f32_e32 v76, v76, v76
	v_max_f32_e32 v68, v68, v68
	v_max_f32_e32 v77, v77, v77
	v_max_f32_e32 v69, v69, v69
	v_max_f32_e32 v78, v78, v78
	v_max_f32_e32 v70, v70, v70
	v_max_f32_e32 v79, v79, v79
	v_med3_f32 v71, v71, s73, v159
	v_med3_f32 v76, v76, s73, v159
	v_med3_f32 v68, v68, s73, v159
	v_med3_f32 v77, v77, s73, v159
	v_med3_f32 v69, v69, s73, v159
	v_med3_f32 v78, v78, s73, v159
	v_med3_f32 v70, v70, s73, v159
	v_med3_f32 v79, v79, s73, v159
	v_mul_f32_e32 v71, 0xbfb8aa3b, v71
	v_mul_f32_e32 v76, 0xbfb8aa3b, v76
	v_mul_f32_e32 v68, 0xbfb8aa3b, v68
	v_mul_f32_e32 v77, 0xbfb8aa3b, v77
	v_mul_f32_e32 v69, 0xbfb8aa3b, v69
	v_mul_f32_e32 v78, 0xbfb8aa3b, v78
	v_mul_f32_e32 v70, 0xbfb8aa3b, v70
	v_mul_f32_e32 v79, 0xbfb8aa3b, v79
	v_exp_f32_e32 v71, v71
	v_exp_f32_e32 v76, v76
	v_exp_f32_e32 v68, v68
	v_exp_f32_e32 v77, v77
	v_exp_f32_e32 v69, v69
	v_exp_f32_e32 v78, v78
	v_exp_f32_e32 v70, v70
	v_exp_f32_e32 v79, v79
	v_add_f32_e32 v71, 1.0, v71
	v_add_f32_e32 v76, 1.0, v76
	v_add_f32_e32 v68, 1.0, v68
	v_add_f32_e32 v77, 1.0, v77
	v_add_f32_e32 v69, 1.0, v69
	v_add_f32_e32 v78, 1.0, v78
	v_add_f32_e32 v70, 1.0, v70
	v_add_f32_e32 v79, 1.0, v79
	v_rcp_f32_e32 v71, v71
	v_rcp_f32_e32 v76, v76
	v_rcp_f32_e32 v68, v68
	v_rcp_f32_e32 v77, v77
	v_rcp_f32_e32 v69, v69
	v_rcp_f32_e32 v78, v78
	v_rcp_f32_e32 v70, v70
	v_rcp_f32_e32 v79, v79
	v_mul_f32_e32 v63, v63, v71
	v_mul_f32_e32 v64, v64, v76
	v_mul_f32_e32 v65, v65, v68
	v_mul_f32_e32 v66, v66, v77
	v_mul_f32_e32 v67, v67, v69
	v_mul_f32_e32 v68, v60, v78
	v_mul_f32_e32 v69, v61, v70
	v_mul_f32_e32 v70, v62, v79
	v_cvt_pk_bf16_f32 v60, v64, v65
	v_cvt_pk_bf16_f32 v61, v66, v67
	v_cvt_pk_bf16_f32 v62, v68, v69
	v_cvt_pk_bf16_f32 v63, v70, v63
	global_store_dwordx4 v[72:73], v[60:63], off
	global_load_dwordx4 v[60:63], v[74:75], off
	v_add_u32_e32 v64, 0x90, v150
	v_ashrrev_i32_e32 v65, 31, v64
	v_lshlrev_b64 v[66:67], 11, v[64:65]
	v_lshl_add_u64 v[66:67], s[46:47], 0, v[66:67]
	v_lshl_add_u64 v[68:69], v[66:67], 0, v[0:1]
	s_waitcnt vmcnt(0)
	v_lshlrev_b32_e32 v75, 16, v63
	v_and_b32_e32 v63, 0xffff0000, v63
	v_lshlrev_b32_e32 v70, 16, v60
	v_and_b32_e32 v60, 0xffff0000, v60
	v_lshlrev_b32_e32 v71, 16, v61
	v_and_b32_e32 v61, 0xffff0000, v61
	v_lshlrev_b32_e32 v74, 16, v62
	v_and_b32_e32 v62, 0xffff0000, v62
	v_max_f32_e32 v63, v63, v63
	v_max_f32_e32 v70, v70, v70
	v_max_f32_e32 v60, v60, v60
	v_max_f32_e32 v71, v71, v71
	v_max_f32_e32 v61, v61, v61
	v_max_f32_e32 v74, v74, v74
	v_max_f32_e32 v62, v62, v62
	v_max_f32_e32 v75, v75, v75
	v_med3_f32 v63, v63, s73, v159
	v_med3_f32 v70, v70, s73, v159
	v_med3_f32 v60, v60, s73, v159
	v_med3_f32 v71, v71, s73, v159
	v_med3_f32 v61, v61, s73, v159
	v_med3_f32 v74, v74, s73, v159
	v_med3_f32 v62, v62, s73, v159
	v_med3_f32 v75, v75, s73, v159
	v_mul_f32_e32 v63, 0xbfb8aa3b, v63
	v_mul_f32_e32 v70, 0xbfb8aa3b, v70
	v_mul_f32_e32 v60, 0xbfb8aa3b, v60
	v_mul_f32_e32 v71, 0xbfb8aa3b, v71
	v_mul_f32_e32 v61, 0xbfb8aa3b, v61
	v_mul_f32_e32 v74, 0xbfb8aa3b, v74
	v_mul_f32_e32 v62, 0xbfb8aa3b, v62
	v_mul_f32_e32 v75, 0xbfb8aa3b, v75
	v_exp_f32_e32 v63, v63
	v_exp_f32_e32 v70, v70
	v_exp_f32_e32 v60, v60
	v_exp_f32_e32 v71, v71
	v_exp_f32_e32 v61, v61
	v_exp_f32_e32 v74, v74
	v_exp_f32_e32 v62, v62
	v_exp_f32_e32 v75, v75
	v_add_f32_e32 v63, 1.0, v63
	v_add_f32_e32 v70, 1.0, v70
	v_add_f32_e32 v60, 1.0, v60
	v_add_f32_e32 v71, 1.0, v71
	v_add_f32_e32 v61, 1.0, v61
	v_add_f32_e32 v74, 1.0, v74
	v_add_f32_e32 v62, 1.0, v62
	v_add_f32_e32 v75, 1.0, v75
	v_rcp_f32_e32 v63, v63
	v_rcp_f32_e32 v70, v70
	v_rcp_f32_e32 v60, v60
	v_rcp_f32_e32 v71, v71
	v_rcp_f32_e32 v61, v61
	v_rcp_f32_e32 v74, v74
	v_rcp_f32_e32 v62, v62
	v_rcp_f32_e32 v75, v75
	v_mul_f32_e32 v55, v55, v63
	v_mul_f32_e32 v56, v56, v70
	v_mul_f32_e32 v57, v57, v60
	v_mul_f32_e32 v58, v58, v71
	v_mul_f32_e32 v59, v59, v61
	v_mul_f32_e32 v60, v52, v74
	v_mul_f32_e32 v61, v53, v62
	v_mul_f32_e32 v62, v54, v75
	v_cvt_pk_bf16_f32 v52, v56, v57
	v_cvt_pk_bf16_f32 v53, v58, v59
	v_cvt_pk_bf16_f32 v54, v60, v61
	v_cvt_pk_bf16_f32 v55, v62, v55
	global_store_dwordx4 v[72:73], v[52:55], off offset:256
	global_load_dwordx4 v[52:55], v[68:69], off
	v_lshlrev_b64 v[56:57], 12, v[64:65]
	v_lshl_add_u64 v[56:57], s[38:39], 0, v[56:57]
	v_lshl_add_u64 v[56:57], v[56:57], 0, v[148:149]
	v_lshl_add_u64 v[58:59], v[66:67], 0, v[2:3]
	s_waitcnt vmcnt(0)
; __device__ __forceinline__ unsigned cvt_pk_bf16(float lo, float hi) { unsigned r; asm volatile("v_cvt_pk_bf16_f32 %0, %1, %2" : "=v"(r) : "v"(lo), "v"(hi)); return r; }
; __device__ __forceinline__ float bflo(unsigned w) { return __uint_as_float(w << 16); }
; __device__ __forceinline__ float bfhi(unsigned w) { return __uint_as_float(w & 0xffff0000u); }
; __device__ __forceinline__ float sigmoidf_(float x) { return __builtin_amdgcn_rcpf(1.f + __expf(-x)); }
;     static __device__ __forceinline__ float cl(float x) { return fminf(fmaxf(x, -30.f), 30.f); }
;     __device__ __forceinline__ void operator()(const f32x4 (&acc)[2][2][4][2], const Unit& u, int wr, int wc, int fr, int fq) const {
;     ...
;             for (int m = 0; m < 4; ++m) { const size_t row = (size_t)(row0 + ai * HALF + m * 16);
; #pragma unroll
;                 for (int bj = 0; bj < 2; ++bj) { const int col = u.pn * BM + bj * HALF + wc * 32 + 8 * fq;
;                     const u32x4 gw = *(const u32x4*)(gate + (size_t)(2 + (col >> 10)) * SEC + row * 1024 + (col & 1023));
;                     const f32x4 v0 = acc[ai][bj][m][0], v1 = acc[ai][bj][m][1];
;                     float r[8];
;                     r[0] = v0[0] * sigmoidf_(cl(bflo(gw.x))); r[1] = v0[1] * sigmoidf_(cl(bfhi(gw.x))); r[2] = v0[2] * sigmoidf_(cl(bflo(gw.y))); r[3] = v0[3] * sigmoidf_(cl(bfhi(gw.y)));
;                     r[4] = v1[0] * sigmoidf_(cl(bflo(gw.z))); r[5] = v1[1] * sigmoidf_(cl(bfhi(gw.z))); r[6] = v1[2] * sigmoidf_(cl(bflo(gw.w))); r[7] = v1[3] * sigmoidf_(cl(bfhi(gw.w)));
;                     u32x4 w; w.x = cvt_pk_bf16(r[0], r[1]); w.y = cvt_pk_bf16(r[2], r[3]); w.z = cvt_pk_bf16(r[4], r[5]); w.w = cvt_pk_bf16(r[6], r[7]);
;                     *(u32x4*)(mix + row * 2048 + col) = w; } }
	v_lshlrev_b32_e32 v63, 16, v55
	v_and_b32_e32 v55, 0xffff0000, v55
	v_lshlrev_b32_e32 v60, 16, v52
	v_and_b32_e32 v52, 0xffff0000, v52
	v_lshlrev_b32_e32 v61, 16, v53
	v_and_b32_e32 v53, 0xffff0000, v53
	v_lshlrev_b32_e32 v62, 16, v54
	v_and_b32_e32 v54, 0xffff0000, v54
	v_max_f32_e32 v55, v55, v55
	v_max_f32_e32 v60, v60, v60
	v_max_f32_e32 v52, v52, v52
	v_max_f32_e32 v61, v61, v61
	v_max_f32_e32 v53, v53, v53
	v_max_f32_e32 v62, v62, v62
	v_max_f32_e32 v54, v54, v54
	v_max_f32_e32 v63, v63, v63
	v_med3_f32 v55, v55, s73, v159
	v_med3_f32 v60, v60, s73, v159
	v_med3_f32 v52, v52, s73, v159
	v_med3_f32 v61, v61, s73, v159
	v_med3_f32 v53, v53, s73, v159
	v_med3_f32 v62, v62, s73, v159
	v_med3_f32 v54, v54, s73, v159
	v_med3_f32 v63, v63, s73, v159
	v_mul_f32_e32 v55, 0xbfb8aa3b, v55
	v_mul_f32_e32 v60, 0xbfb8aa3b, v60
	v_mul_f32_e32 v52, 0xbfb8aa3b, v52
	v_mul_f32_e32 v61, 0xbfb8aa3b, v61
	v_mul_f32_e32 v53, 0xbfb8aa3b, v53
	v_mul_f32_e32 v62, 0xbfb8aa3b, v62
	v_mul_f32_e32 v54, 0xbfb8aa3b, v54
	v_mul_f32_e32 v63, 0xbfb8aa3b, v63
	v_exp_f32_e32 v55, v55
	v_exp_f32_e32 v60, v60
	v_exp_f32_e32 v52, v52
	v_exp_f32_e32 v61, v61
	v_exp_f32_e32 v53, v53
	v_exp_f32_e32 v62, v62
	v_exp_f32_e32 v54, v54
	v_exp_f32_e32 v63, v63
	v_add_f32_e32 v55, 1.0, v55
	v_add_f32_e32 v60, 1.0, v60
	v_add_f32_e32 v52, 1.0, v52
	v_add_f32_e32 v61, 1.0, v61
	v_add_f32_e32 v53, 1.0, v53
	v_add_f32_e32 v62, 1.0, v62
	v_add_f32_e32 v54, 1.0, v54
	v_add_f32_e32 v63, 1.0, v63
	v_rcp_f32_e32 v55, v55
	v_rcp_f32_e32 v60, v60
	v_rcp_f32_e32 v52, v52
	v_rcp_f32_e32 v61, v61
	v_rcp_f32_e32 v53, v53
	v_rcp_f32_e32 v62, v62
	v_rcp_f32_e32 v54, v54
	v_rcp_f32_e32 v63, v63
	v_mul_f32_e32 v47, v47, v55
	v_mul_f32_e32 v48, v48, v60
	v_mul_f32_e32 v49, v49, v52
	v_mul_f32_e32 v50, v50, v61
	v_mul_f32_e32 v51, v51, v53
	v_mul_f32_e32 v52, v44, v62
	v_mul_f32_e32 v53, v45, v54
	v_mul_f32_e32 v54, v46, v63
	v_cvt_pk_bf16_f32 v44, v48, v49
	v_cvt_pk_bf16_f32 v45, v50, v51
	v_cvt_pk_bf16_f32 v46, v52, v53
	v_cvt_pk_bf16_f32 v47, v54, v47
	global_store_dwordx4 v[56:57], v[44:47], off
	global_load_dwordx4 v[44:47], v[58:59], off
	v_add_u32_e32 v48, 0xa0, v150
	v_ashrrev_i32_e32 v49, 31, v48
	v_lshlrev_b64 v[50:51], 11, v[48:49]
	v_lshl_add_u64 v[50:51], s[46:47], 0, v[50:51]
	v_lshl_add_u64 v[52:53], v[50:51], 0, v[0:1]
	s_waitcnt vmcnt(0)
	v_lshlrev_b32_e32 v59, 16, v47
	v_and_b32_e32 v47, 0xffff0000, v47
	v_lshlrev_b32_e32 v54, 16, v44
	v_and_b32_e32 v44, 0xffff0000, v44
	v_lshlrev_b32_e32 v55, 16, v45
	v_and_b32_e32 v45, 0xffff0000, v45
	v_lshlrev_b32_e32 v58, 16, v46
	v_and_b32_e32 v46, 0xffff0000, v46
	v_max_f32_e32 v47, v47, v47
	v_max_f32_e32 v54, v54, v54
	v_max_f32_e32 v44, v44, v44
	v_max_f32_e32 v55, v55, v55
	v_max_f32_e32 v45, v45, v45
	v_max_f32_e32 v58, v58, v58
	v_max_f32_e32 v46, v46, v46
	v_max_f32_e32 v59, v59, v59
	v_med3_f32 v47, v47, s73, v159
	v_med3_f32 v54, v54, s73, v159
	v_med3_f32 v44, v44, s73, v159
	v_med3_f32 v55, v55, s73, v159
	v_med3_f32 v45, v45, s73, v159
	v_med3_f32 v58, v58, s73, v159
	v_med3_f32 v46, v46, s73, v159
	v_med3_f32 v59, v59, s73, v159
	v_mul_f32_e32 v47, 0xbfb8aa3b, v47
	v_mul_f32_e32 v54, 0xbfb8aa3b, v54
	v_mul_f32_e32 v44, 0xbfb8aa3b, v44
	v_mul_f32_e32 v55, 0xbfb8aa3b, v55
	v_mul_f32_e32 v45, 0xbfb8aa3b, v45
	v_mul_f32_e32 v58, 0xbfb8aa3b, v58
	v_mul_f32_e32 v46, 0xbfb8aa3b, v46
	v_mul_f32_e32 v59, 0xbfb8aa3b, v59
	v_exp_f32_e32 v47, v47
	v_exp_f32_e32 v54, v54
	v_exp_f32_e32 v44, v44
	v_exp_f32_e32 v55, v55
	v_exp_f32_e32 v45, v45
	v_exp_f32_e32 v58, v58
	v_exp_f32_e32 v46, v46
	v_exp_f32_e32 v59, v59
	v_add_f32_e32 v47, 1.0, v47
	v_add_f32_e32 v54, 1.0, v54
	v_add_f32_e32 v44, 1.0, v44
	v_add_f32_e32 v55, 1.0, v55
	v_add_f32_e32 v45, 1.0, v45
	v_add_f32_e32 v58, 1.0, v58
	v_add_f32_e32 v46, 1.0, v46
	v_add_f32_e32 v59, 1.0, v59
	v_rcp_f32_e32 v47, v47
	v_rcp_f32_e32 v54, v54
	v_rcp_f32_e32 v44, v44
	v_rcp_f32_e32 v55, v55
	v_rcp_f32_e32 v45, v45
	v_rcp_f32_e32 v58, v58
	v_rcp_f32_e32 v46, v46
	v_rcp_f32_e32 v59, v59
	v_mul_f32_e32 v39, v39, v47
	v_mul_f32_e32 v40, v40, v54
	v_mul_f32_e32 v41, v41, v44
	v_mul_f32_e32 v42, v42, v55
	v_mul_f32_e32 v43, v43, v45
	v_mul_f32_e32 v44, v36, v58
	v_mul_f32_e32 v45, v37, v46
	v_mul_f32_e32 v46, v38, v59
	v_cvt_pk_bf16_f32 v36, v40, v41
	v_cvt_pk_bf16_f32 v37, v42, v43
	v_cvt_pk_bf16_f32 v38, v44, v45
	v_cvt_pk_bf16_f32 v39, v46, v39
	global_store_dwordx4 v[56:57], v[36:39], off offset:256
	global_load_dwordx4 v[36:39], v[52:53], off
	v_lshlrev_b64 v[40:41], 12, v[48:49]
	v_lshl_add_u64 v[40:41], s[38:39], 0, v[40:41]
	v_lshl_add_u64 v[40:41], v[40:41], 0, v[148:149]
	v_lshl_add_u64 v[42:43], v[50:51], 0, v[2:3]
	s_waitcnt vmcnt(0)
; __device__ __forceinline__ unsigned cvt_pk_bf16(float lo, float hi) { unsigned r; asm volatile("v_cvt_pk_bf16_f32 %0, %1, %2" : "=v"(r) : "v"(lo), "v"(hi)); return r; }
; __device__ __forceinline__ float bflo(unsigned w) { return __uint_as_float(w << 16); }
; __device__ __forceinline__ float bfhi(unsigned w) { return __uint_as_float(w & 0xffff0000u); }
; __device__ __forceinline__ float sigmoidf_(float x) { return __builtin_amdgcn_rcpf(1.f + __expf(-x)); }
;     static __device__ __forceinline__ float cl(float x) { return fminf(fmaxf(x, -30.f), 30.f); }
;     __device__ __forceinline__ void operator()(const f32x4 (&acc)[2][2][4][2], const Unit& u, int wr, int wc, int fr, int fq) const {
;     ...
;             for (int m = 0; m < 4; ++m) { const size_t row = (size_t)(row0 + ai * HALF + m * 16);
; #pragma unroll
;                 for (int bj = 0; bj < 2; ++bj) { const int col = u.pn * BM + bj * HALF + wc * 32 + 8 * fq;
;                     const u32x4 gw = *(const u32x4*)(gate + (size_t)(2 + (col >> 10)) * SEC + row * 1024 + (col & 1023));
;                     const f32x4 v0 = acc[ai][bj][m][0], v1 = acc[ai][bj][m][1];
;                     float r[8];
;                     r[0] = v0[0] * sigmoidf_(cl(bflo(gw.x))); r[1] = v0[1] * sigmoidf_(cl(bfhi(gw.x))); r[2] = v0[2] * sigmoidf_(cl(bflo(gw.y))); r[3] = v0[3] * sigmoidf_(cl(bfhi(gw.y)));
;                     r[4] = v1[0] * sigmoidf_(cl(bflo(gw.z))); r[5] = v1[1] * sigmoidf_(cl(bfhi(gw.z))); r[6] = v1[2] * sigmoidf_(cl(bflo(gw.w))); r[7] = v1[3] * sigmoidf_(cl(bfhi(gw.w)));
;                     u32x4 w; w.x = cvt_pk_bf16(r[0], r[1]); w.y = cvt_pk_bf16(r[2], r[3]); w.z = cvt_pk_bf16(r[4], r[5]); w.w = cvt_pk_bf16(r[6], r[7]);
;                     *(u32x4*)(mix + row * 2048 + col) = w; } }
	v_lshlrev_b32_e32 v47, 16, v39
	v_and_b32_e32 v39, 0xffff0000, v39
	v_lshlrev_b32_e32 v44, 16, v36
	v_and_b32_e32 v36, 0xffff0000, v36
	v_lshlrev_b32_e32 v45, 16, v37
	v_and_b32_e32 v37, 0xffff0000, v37
	v_lshlrev_b32_e32 v46, 16, v38
	v_and_b32_e32 v38, 0xffff0000, v38
	v_max_f32_e32 v39, v39, v39
	v_max_f32_e32 v44, v44, v44
	v_max_f32_e32 v36, v36, v36
	v_max_f32_e32 v45, v45, v45
	v_max_f32_e32 v37, v37, v37
	v_max_f32_e32 v46, v46, v46
	v_max_f32_e32 v38, v38, v38
	v_max_f32_e32 v47, v47, v47
	v_med3_f32 v39, v39, s73, v159
	v_med3_f32 v44, v44, s73, v159
	v_med3_f32 v36, v36, s73, v159
	v_med3_f32 v45, v45, s73, v159
	v_med3_f32 v37, v37, s73, v159
	v_med3_f32 v46, v46, s73, v159
	v_med3_f32 v38, v38, s73, v159
	v_med3_f32 v47, v47, s73, v159
	v_mul_f32_e32 v39, 0xbfb8aa3b, v39
	v_mul_f32_e32 v44, 0xbfb8aa3b, v44
	v_mul_f32_e32 v36, 0xbfb8aa3b, v36
	v_mul_f32_e32 v45, 0xbfb8aa3b, v45
	v_mul_f32_e32 v37, 0xbfb8aa3b, v37
	v_mul_f32_e32 v46, 0xbfb8aa3b, v46
	v_mul_f32_e32 v38, 0xbfb8aa3b, v38
	v_mul_f32_e32 v47, 0xbfb8aa3b, v47
	v_exp_f32_e32 v39, v39
	v_exp_f32_e32 v44, v44
	v_exp_f32_e32 v36, v36
	v_exp_f32_e32 v45, v45
	v_exp_f32_e32 v37, v37
	v_exp_f32_e32 v46, v46
	v_exp_f32_e32 v38, v38
	v_exp_f32_e32 v47, v47
	v_add_f32_e32 v39, 1.0, v39
	v_add_f32_e32 v44, 1.0, v44
	v_add_f32_e32 v36, 1.0, v36
	v_add_f32_e32 v45, 1.0, v45
	v_add_f32_e32 v37, 1.0, v37
	v_add_f32_e32 v46, 1.0, v46
	v_add_f32_e32 v38, 1.0, v38
	v_add_f32_e32 v47, 1.0, v47
	v_rcp_f32_e32 v39, v39
	v_rcp_f32_e32 v44, v44
	v_rcp_f32_e32 v36, v36
	v_rcp_f32_e32 v45, v45
	v_rcp_f32_e32 v37, v37
	v_rcp_f32_e32 v46, v46
	v_rcp_f32_e32 v38, v38
	v_rcp_f32_e32 v47, v47
	v_mul_f32_e32 v31, v31, v39
	v_mul_f32_e32 v32, v32, v44
	v_mul_f32_e32 v33, v33, v36
	v_mul_f32_e32 v34, v34, v45
	v_mul_f32_e32 v35, v35, v37
	v_mul_f32_e32 v36, v28, v46
	v_mul_f32_e32 v37, v29, v38
	v_mul_f32_e32 v38, v30, v47
	v_cvt_pk_bf16_f32 v28, v32, v33
	v_cvt_pk_bf16_f32 v29, v34, v35
	v_cvt_pk_bf16_f32 v30, v36, v37
	v_cvt_pk_bf16_f32 v31, v38, v31
	global_store_dwordx4 v[40:41], v[28:31], off
	global_load_dwordx4 v[28:31], v[42:43], off
	v_add_u32_e32 v32, 0xb0, v150
	v_ashrrev_i32_e32 v33, 31, v32
	v_lshlrev_b64 v[34:35], 11, v[32:33]
	v_lshl_add_u64 v[34:35], s[46:47], 0, v[34:35]
	v_lshl_add_u64 v[36:37], v[34:35], 0, v[0:1]
	v_lshl_add_u64 v[2:3], v[34:35], 0, v[2:3]
	s_waitcnt vmcnt(0)
	v_lshlrev_b32_e32 v42, 16, v31
	v_and_b32_e32 v31, 0xffff0000, v31
	v_lshlrev_b32_e32 v0, 16, v28
	v_and_b32_e32 v28, 0xffff0000, v28
	v_lshlrev_b32_e32 v38, 16, v29
	v_and_b32_e32 v29, 0xffff0000, v29
	v_lshlrev_b32_e32 v39, 16, v30
	v_and_b32_e32 v30, 0xffff0000, v30
	v_max_f32_e32 v31, v31, v31
	v_max_f32_e32 v0, v0, v0
	v_max_f32_e32 v28, v28, v28
	v_max_f32_e32 v38, v38, v38
	v_max_f32_e32 v29, v29, v29
	v_max_f32_e32 v39, v39, v39
	v_max_f32_e32 v30, v30, v30
	v_max_f32_e32 v42, v42, v42
	v_med3_f32 v31, v31, s73, v159
	v_med3_f32 v0, v0, s73, v159
	v_med3_f32 v28, v28, s73, v159
	v_med3_f32 v38, v38, s73, v159
	v_med3_f32 v29, v29, s73, v159
	v_med3_f32 v39, v39, s73, v159
	v_med3_f32 v30, v30, s73, v159
	v_med3_f32 v42, v42, s73, v159
	v_mul_f32_e32 v31, 0xbfb8aa3b, v31
	v_mul_f32_e32 v0, 0xbfb8aa3b, v0
	v_mul_f32_e32 v28, 0xbfb8aa3b, v28
	v_mul_f32_e32 v38, 0xbfb8aa3b, v38
	v_mul_f32_e32 v29, 0xbfb8aa3b, v29
	v_mul_f32_e32 v39, 0xbfb8aa3b, v39
	v_mul_f32_e32 v30, 0xbfb8aa3b, v30
	v_mul_f32_e32 v42, 0xbfb8aa3b, v42
	v_exp_f32_e32 v31, v31
	v_exp_f32_e32 v0, v0
	v_exp_f32_e32 v28, v28
	v_exp_f32_e32 v38, v38
	v_exp_f32_e32 v29, v29
	v_exp_f32_e32 v39, v39
	v_exp_f32_e32 v30, v30
	v_exp_f32_e32 v42, v42
	v_add_f32_e32 v31, 1.0, v31
	v_add_f32_e32 v0, 1.0, v0
	v_add_f32_e32 v28, 1.0, v28
	v_add_f32_e32 v38, 1.0, v38
	v_add_f32_e32 v29, 1.0, v29
	v_add_f32_e32 v39, 1.0, v39
	v_add_f32_e32 v30, 1.0, v30
	v_add_f32_e32 v42, 1.0, v42
	v_rcp_f32_e32 v31, v31
	v_rcp_f32_e32 v0, v0
	v_rcp_f32_e32 v28, v28
	v_rcp_f32_e32 v38, v38
	v_rcp_f32_e32 v29, v29
	v_rcp_f32_e32 v39, v39
	v_rcp_f32_e32 v30, v30
	v_rcp_f32_e32 v42, v42
	v_mul_f32_e32 v23, v23, v31
	v_mul_f32_e32 v0, v24, v0
	v_mul_f32_e32 v24, v25, v28
	v_mul_f32_e32 v25, v26, v38
	v_mul_f32_e32 v26, v27, v29
	v_mul_f32_e32 v27, v20, v39
	v_mul_f32_e32 v28, v21, v30
	v_mul_f32_e32 v29, v22, v42
	v_cvt_pk_bf16_f32 v20, v0, v24
	v_cvt_pk_bf16_f32 v21, v25, v26
	v_cvt_pk_bf16_f32 v22, v27, v28
	v_cvt_pk_bf16_f32 v23, v29, v23
	global_store_dwordx4 v[40:41], v[20:23], off offset:256
	global_load_dwordx4 v[20:23], v[36:37], off
	v_lshlrev_b64 v[24:25], 12, v[32:33]
	v_lshl_add_u64 v[24:25], s[38:39], 0, v[24:25]
	v_lshl_add_u64 v[24:25], v[24:25], 0, v[148:149]
	s_waitcnt vmcnt(0)
; __device__ __forceinline__ unsigned cvt_pk_bf16(float lo, float hi) { unsigned r; asm volatile("v_cvt_pk_bf16_f32 %0, %1, %2" : "=v"(r) : "v"(lo), "v"(hi)); return r; }
; __device__ __forceinline__ float bflo(unsigned w) { return __uint_as_float(w << 16); }
; __device__ __forceinline__ float bfhi(unsigned w) { return __uint_as_float(w & 0xffff0000u); }
; __device__ __forceinline__ float sigmoidf_(float x) { return __builtin_amdgcn_rcpf(1.f + __expf(-x)); }
;     static __device__ __forceinline__ float cl(float x) { return fminf(fmaxf(x, -30.f), 30.f); }
; #define PG8_WAIT_V(n) asm volatile("s_waitcnt vmcnt(" #n ")" ::: "memory")
; #define PG8_BAR __builtin_amdgcn_s_barrier()
;     __device__ __forceinline__ void operator()(const f32x4 (&acc)[2][2][4][2], const Unit& u, int wr, int wc, int fr, int fq) const {
;     ...
;                 for (int bj = 0; bj < 2; ++bj) { const int col = u.pn * BM + bj * HALF + wc * 32 + 8 * fq;
;                     const u32x4 gw = *(const u32x4*)(gate + (size_t)(2 + (col >> 10)) * SEC + row * 1024 + (col & 1023));
;                     const f32x4 v0 = acc[ai][bj][m][0], v1 = acc[ai][bj][m][1];
;                     float r[8];
;                     r[0] = v0[0] * sigmoidf_(cl(bflo(gw.x))); r[1] = v0[1] * sigmoidf_(cl(bfhi(gw.x))); r[2] = v0[2] * sigmoidf_(cl(bflo(gw.y))); r[3] = v0[3] * sigmoidf_(cl(bfhi(gw.y)));
;                     r[4] = v1[0] * sigmoidf_(cl(bflo(gw.z))); r[5] = v1[1] * sigmoidf_(cl(bfhi(gw.z))); r[6] = v1[2] * sigmoidf_(cl(bflo(gw.w))); r[7] = v1[3] * sigmoidf_(cl(bfhi(gw.w)));
;                     u32x4 w; w.x = cvt_pk_bf16(r[0], r[1]); w.y = cvt_pk_bf16(r[2], r[3]); w.z = cvt_pk_bf16(r[4], r[5]); w.w = cvt_pk_bf16(r[6], r[7]);
;                     *(u32x4*)(mix + row * 2048 + col) = w; } }
; template <class Epi, class Sched, bool ALIGN_EPI = false, bool SP2 = false>
; __device__ __forceinline__ void gemm_phase(PG8_LAS unsigned char* lds, const Gemm g, const Sched& S, const Epi& E) {
;     ...
;     PG8_WAIT_V(0);
;     if constexpr (!ALIGN_EPI) { if (wr == 0) PG8_BAR; }
;     PG8_BAR;
	v_lshlrev_b32_e32 v28, 16, v23
	v_and_b32_e32 v23, 0xffff0000, v23
	v_lshlrev_b32_e32 v0, 16, v20
	v_and_b32_e32 v20, 0xffff0000, v20
	v_lshlrev_b32_e32 v26, 16, v21
	v_and_b32_e32 v21, 0xffff0000, v21
	v_lshlrev_b32_e32 v27, 16, v22
	v_and_b32_e32 v22, 0xffff0000, v22
	v_max_f32_e32 v23, v23, v23
	v_max_f32_e32 v0, v0, v0
	v_max_f32_e32 v20, v20, v20
	v_max_f32_e32 v26, v26, v26
	v_max_f32_e32 v21, v21, v21
	v_max_f32_e32 v27, v27, v27
	v_max_f32_e32 v22, v22, v22
	v_max_f32_e32 v28, v28, v28
	v_med3_f32 v23, v23, s73, v159
	v_med3_f32 v0, v0, s73, v159
	v_med3_f32 v20, v20, s73, v159
	v_med3_f32 v26, v26, s73, v159
	v_med3_f32 v21, v21, s73, v159
	v_med3_f32 v27, v27, s73, v159
	v_med3_f32 v22, v22, s73, v159
	v_med3_f32 v28, v28, s73, v159
	v_mul_f32_e32 v23, 0xbfb8aa3b, v23
	v_mul_f32_e32 v0, 0xbfb8aa3b, v0
	v_mul_f32_e32 v20, 0xbfb8aa3b, v20
	v_mul_f32_e32 v26, 0xbfb8aa3b, v26
	v_mul_f32_e32 v21, 0xbfb8aa3b, v21
	v_mul_f32_e32 v27, 0xbfb8aa3b, v27
	v_mul_f32_e32 v22, 0xbfb8aa3b, v22
	v_mul_f32_e32 v28, 0xbfb8aa3b, v28
	v_exp_f32_e32 v23, v23
	v_exp_f32_e32 v0, v0
	v_exp_f32_e32 v20, v20
	v_exp_f32_e32 v26, v26
	v_exp_f32_e32 v21, v21
	v_exp_f32_e32 v27, v27
	v_exp_f32_e32 v22, v22
	v_exp_f32_e32 v28, v28
	v_add_f32_e32 v23, 1.0, v23
	v_add_f32_e32 v0, 1.0, v0
	v_add_f32_e32 v20, 1.0, v20
	v_add_f32_e32 v26, 1.0, v26
	v_add_f32_e32 v21, 1.0, v21
	v_add_f32_e32 v27, 1.0, v27
	v_add_f32_e32 v22, 1.0, v22
	v_add_f32_e32 v28, 1.0, v28
	v_rcp_f32_e32 v23, v23
	v_rcp_f32_e32 v0, v0
	v_rcp_f32_e32 v20, v20
	v_rcp_f32_e32 v26, v26
	v_rcp_f32_e32 v21, v21
	v_rcp_f32_e32 v27, v27
	v_rcp_f32_e32 v22, v22
	v_rcp_f32_e32 v28, v28
	v_mul_f32_e32 v15, v15, v23
	v_mul_f32_e32 v0, v16, v0
	v_mul_f32_e32 v16, v17, v20
	v_mul_f32_e32 v17, v18, v26
	v_mul_f32_e32 v18, v19, v21
	v_mul_f32_e32 v19, v12, v27
	v_mul_f32_e32 v20, v13, v22
	v_mul_f32_e32 v21, v14, v28
	v_cvt_pk_bf16_f32 v12, v0, v16
	v_cvt_pk_bf16_f32 v13, v17, v18
	v_cvt_pk_bf16_f32 v14, v19, v20
	v_cvt_pk_bf16_f32 v15, v21, v15
	global_store_dwordx4 v[24:25], v[12:15], off
	global_load_dwordx4 v[12:15], v[2:3], off
	s_waitcnt vmcnt(0)
	v_lshlrev_b32_e32 v0, 16, v12
	v_and_b32_e32 v2, 0xffff0000, v12
	v_lshlrev_b32_e32 v3, 16, v13
	v_and_b32_e32 v12, 0xffff0000, v13
	v_lshlrev_b32_e32 v13, 16, v14
	v_and_b32_e32 v14, 0xffff0000, v14
	v_lshlrev_b32_e32 v16, 16, v15
	v_and_b32_e32 v15, 0xffff0000, v15
	v_max_f32_e32 v2, v2, v2
	v_max_f32_e32 v3, v3, v3
	v_max_f32_e32 v13, v13, v13
	v_max_f32_e32 v14, v14, v14
	v_max_f32_e32 v0, v0, v0
	v_max_f32_e32 v12, v12, v12
	v_max_f32_e32 v16, v16, v16
	v_max_f32_e32 v15, v15, v15
	v_med3_f32 v2, v2, s73, v159
	v_med3_f32 v3, v3, s73, v159
	v_med3_f32 v13, v13, s73, v159
	v_med3_f32 v14, v14, s73, v159
	v_med3_f32 v0, v0, s73, v159
	v_med3_f32 v12, v12, s73, v159
	v_med3_f32 v16, v16, s73, v159
	v_med3_f32 v15, v15, s73, v159
	v_mul_f32_e32 v2, 0xbfb8aa3b, v2
	v_mul_f32_e32 v3, 0xbfb8aa3b, v3
	v_mul_f32_e32 v13, 0xbfb8aa3b, v13
	v_mul_f32_e32 v14, 0xbfb8aa3b, v14
	v_mul_f32_e32 v0, 0xbfb8aa3b, v0
	v_mul_f32_e32 v12, 0xbfb8aa3b, v12
	v_mul_f32_e32 v16, 0xbfb8aa3b, v16
	v_mul_f32_e32 v15, 0xbfb8aa3b, v15
	v_exp_f32_e32 v2, v2
	v_exp_f32_e32 v3, v3
	v_exp_f32_e32 v13, v13
	v_exp_f32_e32 v14, v14
	v_exp_f32_e32 v0, v0
	v_exp_f32_e32 v12, v12
	v_exp_f32_e32 v16, v16
	v_exp_f32_e32 v15, v15
	v_add_f32_e32 v2, 1.0, v2
	v_add_f32_e32 v3, 1.0, v3
	v_add_f32_e32 v13, 1.0, v13
	v_add_f32_e32 v14, 1.0, v14
	v_add_f32_e32 v0, 1.0, v0
	v_add_f32_e32 v12, 1.0, v12
	v_add_f32_e32 v16, 1.0, v16
	v_add_f32_e32 v15, 1.0, v15
	v_rcp_f32_e32 v2, v2
	v_rcp_f32_e32 v3, v3
	v_rcp_f32_e32 v13, v13
	v_rcp_f32_e32 v14, v14
	v_rcp_f32_e32 v0, v0
	v_rcp_f32_e32 v12, v12
	v_rcp_f32_e32 v16, v16
	v_rcp_f32_e32 v15, v15
	v_mul_f32_e32 v2, v9, v2
	v_mul_f32_e32 v3, v10, v3
	v_mul_f32_e32 v4, v4, v13
	v_mul_f32_e32 v5, v5, v14
	v_mul_f32_e32 v0, v8, v0
	v_mul_f32_e32 v8, v11, v12
	v_mul_f32_e32 v6, v6, v16
	v_mul_f32_e32 v7, v7, v15
	v_cvt_pk_bf16_f32 v2, v0, v2
	v_cvt_pk_bf16_f32 v3, v3, v8
	v_cvt_pk_bf16_f32 v4, v4, v5
	v_cvt_pk_bf16_f32 v5, v6, v7
	global_store_dwordx4 v[24:25], v[2:5], off offset:256
	s_cbranch_vccnz .LBB0_619
	s_andn2_b64 vcc, exec, s[6:7]
	s_cbranch_vccnz .LBB0_618
	s_barrier
	s_branch .LBB0_618
.LBB0_635:
	s_setprio 0
	s_waitcnt vmcnt(0)
	s_barrier
.LBB0_636:
	s_cmp_gt_i32 s29, 6
	s_cselect_b64 s[0:1], -1, 0
	s_and_b64 s[4:5], s[4:5], s[0:1]
	s_andn2_b64 vcc, exec, s[4:5]
	s_cbranch_vccnz .LBB0_644
	s_waitcnt vmcnt(0)
	v_cmp_eq_u32_e32 vcc, 0, v220
	s_waitcnt vmcnt(0) lgkmcnt(0)
	s_barrier
	s_and_saveexec_b64 s[4:5], vcc
	s_cbranch_execz .LBB0_643
	s_mov_b64 s[8:9], exec
	buffer_wbl2 sc1
	s_waitcnt vmcnt(0)
	v_mbcnt_lo_u32_b32 v0, s8, 0
	s_add_u32 s6, s34, 0x7e20500
	v_mbcnt_hi_u32_b32 v0, s9, v0
	s_addc_u32 s7, s35, 0
	v_cmp_eq_u32_e32 vcc, 0, v0
	s_and_saveexec_b64 s[10:11], vcc
	s_cbranch_execz .LBB0_640
	s_bcnt1_i32_b64 s3, s[8:9]
	v_mov_b32_e32 v0, 0
	v_mov_b32_e32 v1, s3
	global_atomic_add v0, v1, s[6:7]
